# v112 + merged closing waits (heavy-phase equal priority + single s_waitcnt before pre-MMA barrier)
# baseline (speedup 1.0000x reference)
.LBB0_333:
	s_add_u32 s68, s56, s49
	s_addc_u32 s70, s57, 0
	s_add_u32 s64, s68, 0x100
	s_addc_u32 s65, s70, 0
	s_and_b64 s[62:63], s[60:61], exec
	s_cselect_b32 s65, s18, s65
	s_cselect_b32 s64, s19, s64
	s_add_u32 s49, s54, s49
	s_addc_u32 s62, s55, 0
	s_add_u32 s49, s49, 0x100
	s_addc_u32 s62, s62, 0
	s_add_i32 s80, 0, 0x10000
	s_and_b64 s[60:61], s[60:61], exec
	s_cselect_b32 s67, s33, s62
	s_cselect_b32 s66, s45, s49
	s_add_i32 s61, 0, 0x14000
	s_add_u32 s72, s68, 0x10080
	s_addc_u32 s73, s70, 0
	s_add_i32 s79, s80, s2
	s_add_i32 m0, s4, 0xc000
	s_add_i32 s82, s4, 0xe000
	s_add_i32 s76, s79, 0x2000
	s_add_u32 s70, s66, 0x10000
	v_add_u32_e32 v152, s80, v138
	v_add_u32_e32 v168, s61, v138
	s_addc_u32 s71, s67, 0
	s_add_i32 s78, s61, s2
	ds_read_b128 v[140:143], v152
	ds_read_b128 v[144:147], v152 offset:1024
	ds_read_b128 v[148:151], v152 offset:2048
	ds_read_b128 v[152:155], v152 offset:3072
	ds_read_b128 v[156:159], v168
	ds_read_b128 v[160:163], v168 offset:1024
	ds_read_b128 v[164:167], v168 offset:2048
	ds_read_b128 v[168:171], v168 offset:3072
	s_add_i32 s77, s78, 0x2000
	s_add_i32 s75, 0, 0x18000
	s_add_i32 s74, 0, 0x1c000
	s_add_u32 s62, s64, 0x10000
	s_addc_u32 s63, s65, 0
	s_add_i32 s68, s75, s2
	s_add_i32 s49, s68, 0x2000
	s_add_u32 s60, s66, 0x10080
	s_addc_u32 s61, s67, 0
	s_add_i32 s81, s74, s2
	s_add_i32 s80, s81, 0x2000
	v_lshl_add_u64 v[204:205], s[72:73], 0, v[136:137]
	ds_read_b128 v[172:175], v139
	ds_read_b128 v[176:179], v139 offset:1024
	ds_read_b128 v[180:183], v139 offset:2048
	ds_read_b128 v[184:187], v139 offset:3072
	ds_read_b128 v[188:191], v139 offset:4096
	ds_read_b128 v[192:195], v139 offset:5120
	ds_read_b128 v[196:199], v139 offset:6144
	ds_read_b128 v[214:217], v139 offset:7168
	s_setprio 1
	global_load_lds_dwordx4 v[204:205], off
	v_lshl_add_u64 v[204:205], s[72:73], 0, v[134:135]
	s_mov_b32 m0, s82
	s_nop 0
	global_load_lds_dwordx4 v[204:205], off
	s_waitcnt vmcnt(8) lgkmcnt(0)
	s_barrier
	v_mfma_f32_16x16x32_bf16 v[128:131], v[140:143], v[172:175], v[128:131]
	v_mfma_f32_16x16x32_bf16 v[124:127], v[148:151], v[172:175], v[124:127]
	v_mfma_f32_16x16x32_bf16 v[120:123], v[140:143], v[180:183], v[120:123]
	v_mfma_f32_16x16x32_bf16 v[116:119], v[148:151], v[180:183], v[116:119]
	v_mfma_f32_16x16x32_bf16 v[104:107], v[140:143], v[188:191], v[104:107]
	v_mfma_f32_16x16x32_bf16 v[100:103], v[148:151], v[188:191], v[100:103]
	v_mfma_f32_16x16x32_bf16 v[86:89], v[140:143], v[196:199], v[86:89]
	v_mfma_f32_16x16x32_bf16 v[82:85], v[148:151], v[196:199], v[82:85]
	v_mfma_f32_16x16x32_bf16 v[128:131], v[144:147], v[176:179], v[128:131]
	v_mfma_f32_16x16x32_bf16 v[124:127], v[152:155], v[176:179], v[124:127]
	v_mfma_f32_16x16x32_bf16 v[120:123], v[144:147], v[184:187], v[120:123]
	v_mfma_f32_16x16x32_bf16 v[116:119], v[152:155], v[184:187], v[116:119]
	v_mfma_f32_16x16x32_bf16 v[104:107], v[144:147], v[192:195], v[104:107]
	v_mfma_f32_16x16x32_bf16 v[100:103], v[152:155], v[192:195], v[100:103]
	v_mfma_f32_16x16x32_bf16 v[86:89], v[144:147], v[214:217], v[86:89]
	v_mfma_f32_16x16x32_bf16 v[82:85], v[152:155], v[214:217], v[82:85]
	s_setprio 0
	s_setprio 1
	v_mfma_f32_16x16x32_bf16 v[112:115], v[156:159], v[172:175], v[112:115]
	v_mfma_f32_16x16x32_bf16 v[108:111], v[164:167], v[172:175], v[108:111]
	v_mfma_f32_16x16x32_bf16 v[94:97], v[156:159], v[180:183], v[94:97]
	v_mfma_f32_16x16x32_bf16 v[90:93], v[164:167], v[180:183], v[90:93]
	v_mfma_f32_16x16x32_bf16 v[78:81], v[156:159], v[188:191], v[78:81]
	v_mfma_f32_16x16x32_bf16 v[74:77], v[164:167], v[188:191], v[74:77]
	v_mfma_f32_16x16x32_bf16 v[70:73], v[156:159], v[196:199], v[70:73]
	v_mfma_f32_16x16x32_bf16 v[66:69], v[164:167], v[196:199], v[66:69]
	v_mfma_f32_16x16x32_bf16 v[112:115], v[160:163], v[176:179], v[112:115]
	v_mfma_f32_16x16x32_bf16 v[108:111], v[168:171], v[176:179], v[108:111]
	v_mfma_f32_16x16x32_bf16 v[94:97], v[160:163], v[184:187], v[94:97]
	v_mfma_f32_16x16x32_bf16 v[90:93], v[168:171], v[184:187], v[90:93]
	v_mfma_f32_16x16x32_bf16 v[78:81], v[160:163], v[192:195], v[78:81]
	v_mfma_f32_16x16x32_bf16 v[74:77], v[168:171], v[192:195], v[74:77]
	v_mfma_f32_16x16x32_bf16 v[70:73], v[160:163], v[214:217], v[70:73]
	v_mfma_f32_16x16x32_bf16 v[66:69], v[168:171], v[214:217], v[66:69]
	s_barrier
	s_mov_b32 m0, s79
	v_lshl_add_u64 v[204:205], s[66:67], 0, v[98:99]
	ds_read_b128 v[172:175], v139 offset:16384
	ds_read_b128 v[176:179], v139 offset:17408
	ds_read_b128 v[180:183], v139 offset:18432
	ds_read_b128 v[184:187], v139 offset:19456
	ds_read_b128 v[188:191], v139 offset:20480
	ds_read_b128 v[192:195], v139 offset:21504
	ds_read_b128 v[196:199], v139 offset:22528
	ds_read_b128 v[214:217], v139 offset:23552
	global_load_lds_dwordx4 v[204:205], off
	v_lshl_add_u64 v[206:207], s[66:67], 0, v[132:133]
	s_mov_b32 m0, s76
	v_lshl_add_u64 v[208:209], s[70:71], 0, v[98:99]
	global_load_lds_dwordx4 v[206:207], off
	s_mov_b32 m0, s78
	v_lshl_add_u64 v[210:211], s[64:65], 0, v[134:135]
	global_load_lds_dwordx4 v[208:209], off
	v_lshl_add_u64 v[208:209], s[70:71], 0, v[132:133]
	s_mov_b32 m0, s77
	s_nop 0
	global_load_lds_dwordx4 v[208:209], off
	v_lshl_add_u64 v[208:209], s[64:65], 0, v[136:137]
	s_mov_b32 m0, s4
	s_nop 0
	global_load_lds_dwordx4 v[208:209], off
	s_mov_b32 m0, s7
	s_nop 0
	global_load_lds_dwordx4 v[210:211], off
	s_waitcnt vmcnt(8) lgkmcnt(0)
	s_barrier
	v_mfma_f32_16x16x32_bf16 v[62:65], v[140:143], v[172:175], v[62:65]
	v_mfma_f32_16x16x32_bf16 v[58:61], v[148:151], v[172:175], v[58:61]
	v_mfma_f32_16x16x32_bf16 v[54:57], v[140:143], v[180:183], v[54:57]
	v_mfma_f32_16x16x32_bf16 v[50:53], v[148:151], v[180:183], v[50:53]
	v_mfma_f32_16x16x32_bf16 v[38:41], v[140:143], v[188:191], v[38:41]
	v_mfma_f32_16x16x32_bf16 v[34:37], v[148:151], v[188:191], v[34:37]
	v_mfma_f32_16x16x32_bf16 v[22:25], v[140:143], v[196:199], v[22:25]
	v_mfma_f32_16x16x32_bf16 v[18:21], v[148:151], v[196:199], v[18:21]
	v_mfma_f32_16x16x32_bf16 v[62:65], v[144:147], v[176:179], v[62:65]
	v_mfma_f32_16x16x32_bf16 v[58:61], v[152:155], v[176:179], v[58:61]
	v_mfma_f32_16x16x32_bf16 v[54:57], v[144:147], v[184:187], v[54:57]
	v_mfma_f32_16x16x32_bf16 v[50:53], v[152:155], v[184:187], v[50:53]
	v_mfma_f32_16x16x32_bf16 v[38:41], v[144:147], v[192:195], v[38:41]
	v_mfma_f32_16x16x32_bf16 v[34:37], v[152:155], v[192:195], v[34:37]
	v_mfma_f32_16x16x32_bf16 v[22:25], v[144:147], v[214:217], v[22:25]
	v_mfma_f32_16x16x32_bf16 v[18:21], v[152:155], v[214:217], v[18:21]
	s_setprio 0
	s_setprio 1
	v_mfma_f32_16x16x32_bf16 v[46:49], v[156:159], v[172:175], v[46:49]
	v_mfma_f32_16x16x32_bf16 v[42:45], v[164:167], v[172:175], v[42:45]
	v_mfma_f32_16x16x32_bf16 v[30:33], v[156:159], v[180:183], v[30:33]
	v_mfma_f32_16x16x32_bf16 v[26:29], v[164:167], v[180:183], v[26:29]
	v_mfma_f32_16x16x32_bf16 v[14:17], v[156:159], v[188:191], v[14:17]
	v_mfma_f32_16x16x32_bf16 v[10:13], v[164:167], v[188:191], v[10:13]
	v_mfma_f32_16x16x32_bf16 v[6:9], v[156:159], v[196:199], v[6:9]
	v_mfma_f32_16x16x32_bf16 v[2:5], v[164:167], v[196:199], v[2:5]
	v_mfma_f32_16x16x32_bf16 v[46:49], v[160:163], v[176:179], v[46:49]
	v_mfma_f32_16x16x32_bf16 v[42:45], v[168:171], v[176:179], v[42:45]
	v_mfma_f32_16x16x32_bf16 v[30:33], v[160:163], v[184:187], v[30:33]
	v_mfma_f32_16x16x32_bf16 v[26:29], v[168:171], v[184:187], v[26:29]
	v_mfma_f32_16x16x32_bf16 v[14:17], v[160:163], v[192:195], v[14:17]
	v_mfma_f32_16x16x32_bf16 v[10:13], v[168:171], v[192:195], v[10:13]
	v_mfma_f32_16x16x32_bf16 v[6:9], v[160:163], v[214:217], v[6:9]
	v_mfma_f32_16x16x32_bf16 v[2:5], v[168:171], v[214:217], v[2:5]
	s_setprio 0
	s_barrier
	v_add_u32_e32 v152, s75, v138
	v_add_u32_e32 v168, s74, v138
	ds_read_b128 v[140:143], v152
	ds_read_b128 v[144:147], v152 offset:1024
	ds_read_b128 v[148:151], v152 offset:2048
	ds_read_b128 v[152:155], v152 offset:3072
	ds_read_b128 v[156:159], v168
	ds_read_b128 v[160:163], v168 offset:1024
	ds_read_b128 v[164:167], v168 offset:2048
	ds_read_b128 v[168:171], v168 offset:3072
	s_mov_b32 m0, s8
	v_lshl_add_u64 v[218:219], s[62:63], 0, v[136:137]
	ds_read_b128 v[172:175], v139 offset:32768
	ds_read_b128 v[176:179], v139 offset:33792
	ds_read_b128 v[180:183], v139 offset:34816
	ds_read_b128 v[184:187], v139 offset:35840
	ds_read_b128 v[188:191], v139 offset:36864
	ds_read_b128 v[192:195], v139 offset:37888
	ds_read_b128 v[196:199], v139 offset:38912
	ds_read_b128 v[214:217], v139 offset:39936
	s_setprio 1
	global_load_lds_dwordx4 v[218:219], off
	v_lshl_add_u64 v[218:219], s[62:63], 0, v[134:135]
	s_mov_b32 m0, s9
	s_nop 0
	global_load_lds_dwordx4 v[218:219], off
	s_waitcnt vmcnt(8) lgkmcnt(0)
	s_barrier
	v_mfma_f32_16x16x32_bf16 v[128:131], v[140:143], v[172:175], v[128:131]
	v_mfma_f32_16x16x32_bf16 v[124:127], v[148:151], v[172:175], v[124:127]
	v_mfma_f32_16x16x32_bf16 v[120:123], v[140:143], v[180:183], v[120:123]
	v_mfma_f32_16x16x32_bf16 v[116:119], v[148:151], v[180:183], v[116:119]
	v_mfma_f32_16x16x32_bf16 v[104:107], v[140:143], v[188:191], v[104:107]
	v_mfma_f32_16x16x32_bf16 v[100:103], v[148:151], v[188:191], v[100:103]
	v_mfma_f32_16x16x32_bf16 v[86:89], v[140:143], v[196:199], v[86:89]
	v_mfma_f32_16x16x32_bf16 v[82:85], v[148:151], v[196:199], v[82:85]
	v_mfma_f32_16x16x32_bf16 v[128:131], v[144:147], v[176:179], v[128:131]
	v_mfma_f32_16x16x32_bf16 v[124:127], v[152:155], v[176:179], v[124:127]
	v_mfma_f32_16x16x32_bf16 v[120:123], v[144:147], v[184:187], v[120:123]
	v_mfma_f32_16x16x32_bf16 v[116:119], v[152:155], v[184:187], v[116:119]
	v_mfma_f32_16x16x32_bf16 v[104:107], v[144:147], v[192:195], v[104:107]
	v_mfma_f32_16x16x32_bf16 v[100:103], v[152:155], v[192:195], v[100:103]
	v_mfma_f32_16x16x32_bf16 v[86:89], v[144:147], v[214:217], v[86:89]
	v_mfma_f32_16x16x32_bf16 v[82:85], v[152:155], v[214:217], v[82:85]
	s_setprio 0
	s_setprio 1
	v_mfma_f32_16x16x32_bf16 v[112:115], v[156:159], v[172:175], v[112:115]
	v_mfma_f32_16x16x32_bf16 v[108:111], v[164:167], v[172:175], v[108:111]
	v_mfma_f32_16x16x32_bf16 v[94:97], v[156:159], v[180:183], v[94:97]
	v_mfma_f32_16x16x32_bf16 v[90:93], v[164:167], v[180:183], v[90:93]
	v_mfma_f32_16x16x32_bf16 v[78:81], v[156:159], v[188:191], v[78:81]
	v_mfma_f32_16x16x32_bf16 v[74:77], v[164:167], v[188:191], v[74:77]
	v_mfma_f32_16x16x32_bf16 v[70:73], v[156:159], v[196:199], v[70:73]
	v_mfma_f32_16x16x32_bf16 v[66:69], v[164:167], v[196:199], v[66:69]
	v_mfma_f32_16x16x32_bf16 v[112:115], v[160:163], v[176:179], v[112:115]
	v_mfma_f32_16x16x32_bf16 v[108:111], v[168:171], v[176:179], v[108:111]
	v_mfma_f32_16x16x32_bf16 v[94:97], v[160:163], v[184:187], v[94:97]
	v_mfma_f32_16x16x32_bf16 v[90:93], v[168:171], v[184:187], v[90:93]
	v_mfma_f32_16x16x32_bf16 v[78:81], v[160:163], v[192:195], v[78:81]
	v_mfma_f32_16x16x32_bf16 v[74:77], v[168:171], v[192:195], v[74:77]
	v_mfma_f32_16x16x32_bf16 v[70:73], v[160:163], v[214:217], v[70:73]
	v_mfma_f32_16x16x32_bf16 v[66:69], v[168:171], v[214:217], v[66:69]
	s_barrier
	s_mov_b32 m0, s68
	v_lshl_add_u64 v[204:205], v[204:205], 0, s[28:29]
	ds_read_b128 v[172:175], v139 offset:49152
	ds_read_b128 v[176:179], v139 offset:50176
	ds_read_b128 v[180:183], v139 offset:51200
	ds_read_b128 v[184:187], v139 offset:52224
	ds_read_b128 v[188:191], v139 offset:53248
	ds_read_b128 v[192:195], v139 offset:54272
	ds_read_b128 v[196:199], v139 offset:55296
	ds_read_b128 v[214:217], v139 offset:56320
	global_load_lds_dwordx4 v[204:205], off
	v_lshl_add_u64 v[204:205], v[206:207], 0, s[28:29]
	s_mov_b32 m0, s49
	s_nop 0
	global_load_lds_dwordx4 v[204:205], off
	v_lshl_add_u64 v[204:205], s[60:61], 0, v[98:99]
	s_mov_b32 m0, s81
	s_nop 0
	global_load_lds_dwordx4 v[204:205], off
	v_lshl_add_u64 v[204:205], s[60:61], 0, v[132:133]
	s_mov_b32 m0, s80
	s_nop 0
	global_load_lds_dwordx4 v[204:205], off
	v_lshl_add_u64 v[204:205], v[208:209], 0, s[28:29]
	s_mov_b32 m0, s10
	s_nop 0
	global_load_lds_dwordx4 v[204:205], off
	v_lshl_add_u64 v[204:205], v[210:211], 0, s[28:29]
	s_mov_b32 m0, s11
	s_nop 0
	global_load_lds_dwordx4 v[204:205], off
	s_waitcnt vmcnt(8) lgkmcnt(0)
	s_barrier
	v_mfma_f32_16x16x32_bf16 v[62:65], v[140:143], v[172:175], v[62:65]
	v_mfma_f32_16x16x32_bf16 v[58:61], v[148:151], v[172:175], v[58:61]
	v_mfma_f32_16x16x32_bf16 v[54:57], v[140:143], v[180:183], v[54:57]
	v_mfma_f32_16x16x32_bf16 v[50:53], v[148:151], v[180:183], v[50:53]
	v_mfma_f32_16x16x32_bf16 v[38:41], v[140:143], v[188:191], v[38:41]
	v_mfma_f32_16x16x32_bf16 v[34:37], v[148:151], v[188:191], v[34:37]
	v_mfma_f32_16x16x32_bf16 v[22:25], v[140:143], v[196:199], v[22:25]
	v_mfma_f32_16x16x32_bf16 v[18:21], v[148:151], v[196:199], v[18:21]
	v_mfma_f32_16x16x32_bf16 v[62:65], v[144:147], v[176:179], v[62:65]
	v_mfma_f32_16x16x32_bf16 v[58:61], v[152:155], v[176:179], v[58:61]
	v_mfma_f32_16x16x32_bf16 v[54:57], v[144:147], v[184:187], v[54:57]
	v_mfma_f32_16x16x32_bf16 v[50:53], v[152:155], v[184:187], v[50:53]
	v_mfma_f32_16x16x32_bf16 v[38:41], v[144:147], v[192:195], v[38:41]
	v_mfma_f32_16x16x32_bf16 v[34:37], v[152:155], v[192:195], v[34:37]
	v_mfma_f32_16x16x32_bf16 v[22:25], v[144:147], v[214:217], v[22:25]
	v_mfma_f32_16x16x32_bf16 v[18:21], v[152:155], v[214:217], v[18:21]
	s_setprio 0
	s_setprio 1
	v_mfma_f32_16x16x32_bf16 v[46:49], v[156:159], v[172:175], v[46:49]
	v_mfma_f32_16x16x32_bf16 v[42:45], v[164:167], v[172:175], v[42:45]
	v_mfma_f32_16x16x32_bf16 v[30:33], v[156:159], v[180:183], v[30:33]
	v_mfma_f32_16x16x32_bf16 v[26:29], v[164:167], v[180:183], v[26:29]
	v_mfma_f32_16x16x32_bf16 v[14:17], v[156:159], v[188:191], v[14:17]
	v_mfma_f32_16x16x32_bf16 v[10:13], v[164:167], v[188:191], v[10:13]
	v_mfma_f32_16x16x32_bf16 v[6:9], v[156:159], v[196:199], v[6:9]
	v_mfma_f32_16x16x32_bf16 v[2:5], v[164:167], v[196:199], v[2:5]
	v_mfma_f32_16x16x32_bf16 v[46:49], v[160:163], v[176:179], v[46:49]
	v_mfma_f32_16x16x32_bf16 v[42:45], v[168:171], v[176:179], v[42:45]
	v_mfma_f32_16x16x32_bf16 v[30:33], v[160:163], v[184:187], v[30:33]
	v_mfma_f32_16x16x32_bf16 v[26:29], v[168:171], v[184:187], v[26:29]
	v_mfma_f32_16x16x32_bf16 v[14:17], v[160:163], v[192:195], v[14:17]
	v_mfma_f32_16x16x32_bf16 v[10:13], v[168:171], v[192:195], v[10:13]
	v_mfma_f32_16x16x32_bf16 v[6:9], v[160:163], v[214:217], v[6:9]
	v_mfma_f32_16x16x32_bf16 v[2:5], v[168:171], v[214:217], v[2:5]
	s_setprio 0
	s_barrier
	s_movk_i32 s49, 0x100
	s_andn2_b64 vcc, exec, s[58:59]
	s_mov_b64 s[60:61], -1
	s_mov_b64 s[58:59], 0
	s_cbranch_vccz .LBB0_333
	s_and_b64 vcc, exec, s[40:41]
	s_cbranch_vccz .LBB0_336
	s_barrier

.LBB0_438:
	s_add_u32 s42, s40, 0xfffc0080
	s_addc_u32 s43, s41, -1
	s_add_i32 s67, 0, 0x10000
	s_cmp_eq_u32 s66, 12
	s_cselect_b32 s45, s1, s43
	s_cselect_b32 s44, s49, s42
	s_cselect_b32 s43, s55, s65
	s_cselect_b32 s42, s63, s64
	s_add_i32 s72, 0, 0x14000
	v_add_u32_e32 v108, s67, v162
	v_add_u32_e32 v160, s72, v162
	ds_read_b128 v[90:93], v108
	ds_read_b128 v[94:97], v108 offset:1024
	ds_read_b128 v[100:103], v108 offset:2048
	ds_read_b128 v[108:111], v108 offset:3072
	ds_read_b128 v[166:169], v160
	ds_read_b128 v[170:173], v160 offset:1024
	ds_read_b128 v[174:177], v160 offset:2048
	ds_read_b128 v[178:181], v160 offset:3072
	v_lshl_add_u64 v[160:161], s[40:41], 0, v[156:157]
	s_add_i32 m0, s8, 0xc000
	ds_read_b128 v[182:185], v163
	ds_read_b128 v[186:189], v163 offset:1024
	ds_read_b128 v[190:193], v163 offset:2048
	ds_read_b128 v[194:197], v163 offset:3072
	ds_read_b128 v[214:217], v163 offset:4096
	ds_read_b128 v[218:221], v163 offset:5120
	ds_read_b128 v[222:225], v163 offset:6144
	ds_read_b128 v[226:229], v163 offset:7168
	s_setprio 1
	global_load_lds_dwordx4 v[160:161], off
	v_lshl_add_u64 v[160:161], s[40:41], 0, v[158:159]
	s_add_i32 m0, s8, 0xe000
	s_nop 0
	global_load_lds_dwordx4 v[160:161], off
	s_waitcnt vmcnt(8) lgkmcnt(0)
	s_barrier
	v_mfma_f32_16x16x32_bf16 v[144:147], v[90:93], v[182:185], v[144:147]
	v_mfma_f32_16x16x32_bf16 v[140:143], v[100:103], v[182:185], v[140:143]
	v_mfma_f32_16x16x32_bf16 v[128:131], v[90:93], v[190:193], v[128:131]
	v_mfma_f32_16x16x32_bf16 v[124:127], v[100:103], v[190:193], v[124:127]
	v_mfma_f32_16x16x32_bf16 v[112:115], v[90:93], v[214:217], v[112:115]
	v_mfma_f32_16x16x32_bf16 v[104:107], v[100:103], v[214:217], v[104:107]
	v_mfma_f32_16x16x32_bf16 v[78:81], v[90:93], v[222:225], v[78:81]
	v_mfma_f32_16x16x32_bf16 v[74:77], v[100:103], v[222:225], v[74:77]
	v_mfma_f32_16x16x32_bf16 v[144:147], v[94:97], v[186:189], v[144:147]
	v_mfma_f32_16x16x32_bf16 v[140:143], v[108:111], v[186:189], v[140:143]
	v_mfma_f32_16x16x32_bf16 v[128:131], v[94:97], v[194:197], v[128:131]
	v_mfma_f32_16x16x32_bf16 v[124:127], v[108:111], v[194:197], v[124:127]
	v_mfma_f32_16x16x32_bf16 v[112:115], v[94:97], v[218:221], v[112:115]
	v_mfma_f32_16x16x32_bf16 v[104:107], v[108:111], v[218:221], v[104:107]
	v_mfma_f32_16x16x32_bf16 v[78:81], v[94:97], v[226:229], v[78:81]
	v_mfma_f32_16x16x32_bf16 v[74:77], v[108:111], v[226:229], v[74:77]
	s_setprio 0
	s_setprio 1
	v_mfma_f32_16x16x32_bf16 v[136:139], v[166:169], v[182:185], v[136:139]
	v_mfma_f32_16x16x32_bf16 v[132:135], v[174:177], v[182:185], v[132:135]
	v_mfma_f32_16x16x32_bf16 v[120:123], v[166:169], v[190:193], v[120:123]
	v_mfma_f32_16x16x32_bf16 v[116:119], v[174:177], v[190:193], v[116:119]
	v_mfma_f32_16x16x32_bf16 v[86:89], v[166:169], v[214:217], v[86:89]
	v_mfma_f32_16x16x32_bf16 v[82:85], v[174:177], v[214:217], v[82:85]
	v_mfma_f32_16x16x32_bf16 v[70:73], v[166:169], v[222:225], v[70:73]
	v_mfma_f32_16x16x32_bf16 v[66:69], v[174:177], v[222:225], v[66:69]
	v_mfma_f32_16x16x32_bf16 v[136:139], v[170:173], v[186:189], v[136:139]
	v_mfma_f32_16x16x32_bf16 v[132:135], v[178:181], v[186:189], v[132:135]
	v_mfma_f32_16x16x32_bf16 v[120:123], v[170:173], v[194:197], v[120:123]
	v_mfma_f32_16x16x32_bf16 v[116:119], v[178:181], v[194:197], v[116:119]
	v_mfma_f32_16x16x32_bf16 v[86:89], v[170:173], v[218:221], v[86:89]
	v_mfma_f32_16x16x32_bf16 v[82:85], v[178:181], v[218:221], v[82:85]
	v_mfma_f32_16x16x32_bf16 v[70:73], v[170:173], v[226:229], v[70:73]
	v_mfma_f32_16x16x32_bf16 v[66:69], v[178:181], v[226:229], v[66:69]
	s_barrier
	s_add_i32 s67, s67, s7
	v_lshl_add_u64 v[160:161], s[42:43], 0, v[98:99]
	s_mov_b32 m0, s67
	ds_read_b128 v[182:185], v163 offset:16384
	ds_read_b128 v[186:189], v163 offset:17408
	ds_read_b128 v[190:193], v163 offset:18432
	ds_read_b128 v[194:197], v163 offset:19456
	ds_read_b128 v[214:217], v163 offset:20480
	ds_read_b128 v[218:221], v163 offset:21504
	ds_read_b128 v[222:225], v163 offset:22528
	ds_read_b128 v[226:229], v163 offset:23552
	global_load_lds_dwordx4 v[160:161], off
	s_add_i32 m0, s67, 0x2000
	s_add_u32 s70, s42, 0x40000
	v_lshl_add_u64 v[198:199], s[42:43], 0, v[152:153]
	s_addc_u32 s71, s43, 0
	s_add_i32 s67, s72, s7
	global_load_lds_dwordx4 v[198:199], off
	v_lshl_add_u64 v[204:205], s[70:71], 0, v[98:99]
	s_mov_b32 m0, s67
	v_lshl_add_u64 v[206:207], s[44:45], 0, v[150:151]
	global_load_lds_dwordx4 v[204:205], off
	v_lshl_add_u64 v[204:205], s[70:71], 0, v[152:153]
	s_add_i32 m0, s67, 0x2000
	s_nop 0
	global_load_lds_dwordx4 v[204:205], off
	v_lshl_add_u64 v[204:205], s[44:45], 0, v[148:149]
	s_mov_b32 m0, s8
	s_nop 0
	global_load_lds_dwordx4 v[204:205], off
	s_mov_b32 m0, s9
	s_nop 0
	global_load_lds_dwordx4 v[206:207], off
	s_waitcnt vmcnt(8) lgkmcnt(0)
	s_barrier
	v_mfma_f32_16x16x32_bf16 v[62:65], v[90:93], v[182:185], v[62:65]
	v_mfma_f32_16x16x32_bf16 v[58:61], v[100:103], v[182:185], v[58:61]
	v_mfma_f32_16x16x32_bf16 v[46:49], v[90:93], v[190:193], v[46:49]
	v_mfma_f32_16x16x32_bf16 v[42:45], v[100:103], v[190:193], v[42:45]
	v_mfma_f32_16x16x32_bf16 v[30:33], v[90:93], v[214:217], v[30:33]
	v_mfma_f32_16x16x32_bf16 v[26:29], v[100:103], v[214:217], v[26:29]
	v_mfma_f32_16x16x32_bf16 v[14:17], v[90:93], v[222:225], v[14:17]
	v_mfma_f32_16x16x32_bf16 v[10:13], v[100:103], v[222:225], v[10:13]
	v_mfma_f32_16x16x32_bf16 v[62:65], v[94:97], v[186:189], v[62:65]
	v_mfma_f32_16x16x32_bf16 v[58:61], v[108:111], v[186:189], v[58:61]
	v_mfma_f32_16x16x32_bf16 v[46:49], v[94:97], v[194:197], v[46:49]
	v_mfma_f32_16x16x32_bf16 v[42:45], v[108:111], v[194:197], v[42:45]
	v_mfma_f32_16x16x32_bf16 v[30:33], v[94:97], v[218:221], v[30:33]
	v_mfma_f32_16x16x32_bf16 v[26:29], v[108:111], v[218:221], v[26:29]
	v_mfma_f32_16x16x32_bf16 v[14:17], v[94:97], v[226:229], v[14:17]
	v_mfma_f32_16x16x32_bf16 v[10:13], v[108:111], v[226:229], v[10:13]
	s_setprio 0
	s_setprio 1
	v_mfma_f32_16x16x32_bf16 v[54:57], v[166:169], v[182:185], v[54:57]
	v_mfma_f32_16x16x32_bf16 v[50:53], v[174:177], v[182:185], v[50:53]
	v_mfma_f32_16x16x32_bf16 v[38:41], v[166:169], v[190:193], v[38:41]
	v_mfma_f32_16x16x32_bf16 v[34:37], v[174:177], v[190:193], v[34:37]
	v_mfma_f32_16x16x32_bf16 v[22:25], v[166:169], v[214:217], v[22:25]
	v_mfma_f32_16x16x32_bf16 v[18:21], v[174:177], v[214:217], v[18:21]
	v_mfma_f32_16x16x32_bf16 v[6:9], v[166:169], v[222:225], v[6:9]
	v_mfma_f32_16x16x32_bf16 v[2:5], v[174:177], v[222:225], v[2:5]
	v_mfma_f32_16x16x32_bf16 v[54:57], v[170:173], v[186:189], v[54:57]
	v_mfma_f32_16x16x32_bf16 v[50:53], v[178:181], v[186:189], v[50:53]
	v_mfma_f32_16x16x32_bf16 v[38:41], v[170:173], v[194:197], v[38:41]
	v_mfma_f32_16x16x32_bf16 v[34:37], v[178:181], v[194:197], v[34:37]
	v_mfma_f32_16x16x32_bf16 v[22:25], v[170:173], v[218:221], v[22:25]
	v_mfma_f32_16x16x32_bf16 v[18:21], v[178:181], v[218:221], v[18:21]
	v_mfma_f32_16x16x32_bf16 v[6:9], v[170:173], v[226:229], v[6:9]
	v_mfma_f32_16x16x32_bf16 v[2:5], v[178:181], v[226:229], v[2:5]
	s_setprio 0
	s_barrier
	s_add_i32 s67, 0, 0x18000
	s_add_i32 s70, 0, 0x1c000
	v_add_u32_e32 v108, s67, v162
	v_add_u32_e32 v165, s70, v162
	ds_read_b128 v[90:93], v108
	ds_read_b128 v[94:97], v108 offset:1024
	ds_read_b128 v[100:103], v108 offset:2048
	ds_read_b128 v[108:111], v108 offset:3072
	ds_read_b128 v[166:169], v165
	ds_read_b128 v[170:173], v165 offset:1024
	ds_read_b128 v[174:177], v165 offset:2048
	ds_read_b128 v[178:181], v165 offset:3072
	s_add_u32 s44, s44, 0x40000
	s_addc_u32 s45, s45, 0
	s_mov_b32 m0, s10
	v_lshl_add_u64 v[208:209], s[44:45], 0, v[148:149]
	ds_read_b128 v[182:185], v163 offset:32768
	ds_read_b128 v[186:189], v163 offset:33792
	ds_read_b128 v[190:193], v163 offset:34816
	ds_read_b128 v[194:197], v163 offset:35840
	ds_read_b128 v[214:217], v163 offset:36864
	ds_read_b128 v[218:221], v163 offset:37888
	ds_read_b128 v[222:225], v163 offset:38912
	ds_read_b128 v[226:229], v163 offset:39936
	s_setprio 1
	global_load_lds_dwordx4 v[208:209], off
	v_lshl_add_u64 v[208:209], s[44:45], 0, v[150:151]
	s_mov_b32 m0, s11
	s_nop 0
	global_load_lds_dwordx4 v[208:209], off
	s_waitcnt vmcnt(8) lgkmcnt(0)
	s_barrier
	v_mfma_f32_16x16x32_bf16 v[144:147], v[90:93], v[182:185], v[144:147]
	v_mfma_f32_16x16x32_bf16 v[140:143], v[100:103], v[182:185], v[140:143]
	v_mfma_f32_16x16x32_bf16 v[128:131], v[90:93], v[190:193], v[128:131]
	v_mfma_f32_16x16x32_bf16 v[124:127], v[100:103], v[190:193], v[124:127]
	v_mfma_f32_16x16x32_bf16 v[112:115], v[90:93], v[214:217], v[112:115]
	v_mfma_f32_16x16x32_bf16 v[104:107], v[100:103], v[214:217], v[104:107]
	v_mfma_f32_16x16x32_bf16 v[78:81], v[90:93], v[222:225], v[78:81]
	v_mfma_f32_16x16x32_bf16 v[74:77], v[100:103], v[222:225], v[74:77]
	v_mfma_f32_16x16x32_bf16 v[144:147], v[94:97], v[186:189], v[144:147]
	v_mfma_f32_16x16x32_bf16 v[140:143], v[108:111], v[186:189], v[140:143]
	v_mfma_f32_16x16x32_bf16 v[128:131], v[94:97], v[194:197], v[128:131]
	v_mfma_f32_16x16x32_bf16 v[124:127], v[108:111], v[194:197], v[124:127]
	v_mfma_f32_16x16x32_bf16 v[112:115], v[94:97], v[218:221], v[112:115]
	v_mfma_f32_16x16x32_bf16 v[104:107], v[108:111], v[218:221], v[104:107]
	v_mfma_f32_16x16x32_bf16 v[78:81], v[94:97], v[226:229], v[78:81]
	v_mfma_f32_16x16x32_bf16 v[74:77], v[108:111], v[226:229], v[74:77]
	s_setprio 0
	s_setprio 1
	v_mfma_f32_16x16x32_bf16 v[136:139], v[166:169], v[182:185], v[136:139]
	v_mfma_f32_16x16x32_bf16 v[132:135], v[174:177], v[182:185], v[132:135]
	v_mfma_f32_16x16x32_bf16 v[120:123], v[166:169], v[190:193], v[120:123]
	v_mfma_f32_16x16x32_bf16 v[116:119], v[174:177], v[190:193], v[116:119]
	v_mfma_f32_16x16x32_bf16 v[86:89], v[166:169], v[214:217], v[86:89]
	v_mfma_f32_16x16x32_bf16 v[82:85], v[174:177], v[214:217], v[82:85]
	v_mfma_f32_16x16x32_bf16 v[70:73], v[166:169], v[222:225], v[70:73]
	v_mfma_f32_16x16x32_bf16 v[66:69], v[174:177], v[222:225], v[66:69]
	v_mfma_f32_16x16x32_bf16 v[136:139], v[170:173], v[186:189], v[136:139]
	v_mfma_f32_16x16x32_bf16 v[132:135], v[178:181], v[186:189], v[132:135]
	v_mfma_f32_16x16x32_bf16 v[120:123], v[170:173], v[194:197], v[120:123]
	v_mfma_f32_16x16x32_bf16 v[116:119], v[178:181], v[194:197], v[116:119]
	v_mfma_f32_16x16x32_bf16 v[86:89], v[170:173], v[218:221], v[86:89]
	v_mfma_f32_16x16x32_bf16 v[82:85], v[178:181], v[218:221], v[82:85]
	v_mfma_f32_16x16x32_bf16 v[70:73], v[170:173], v[226:229], v[70:73]
	v_mfma_f32_16x16x32_bf16 v[66:69], v[178:181], v[226:229], v[66:69]
	s_barrier
	s_add_i32 s44, s67, s7
	v_lshl_add_u64 v[160:161], v[160:161], 0, s[28:29]
	s_mov_b32 m0, s44
	ds_read_b128 v[182:185], v163 offset:49152
	ds_read_b128 v[186:189], v163 offset:50176
	ds_read_b128 v[190:193], v163 offset:51200
	ds_read_b128 v[194:197], v163 offset:52224
	ds_read_b128 v[214:217], v163 offset:53248
	ds_read_b128 v[218:221], v163 offset:54272
	ds_read_b128 v[222:225], v163 offset:55296
	ds_read_b128 v[226:229], v163 offset:56320
	global_load_lds_dwordx4 v[160:161], off
	s_add_i32 m0, s44, 0x2000
	s_add_u32 s42, s42, 0x40080
	v_lshl_add_u64 v[160:161], v[198:199], 0, s[28:29]
	s_addc_u32 s43, s43, 0
	s_add_i32 s44, s70, s7
	global_load_lds_dwordx4 v[160:161], off
	v_lshl_add_u64 v[160:161], s[42:43], 0, v[98:99]
	s_mov_b32 m0, s44
	s_nop 0
	global_load_lds_dwordx4 v[160:161], off
	v_lshl_add_u64 v[160:161], s[42:43], 0, v[152:153]
	s_add_i32 m0, s44, 0x2000
	s_nop 0
	global_load_lds_dwordx4 v[160:161], off
	v_lshl_add_u64 v[160:161], v[204:205], 0, s[28:29]
	s_mov_b32 m0, s16
	s_nop 0
	global_load_lds_dwordx4 v[160:161], off
	v_lshl_add_u64 v[160:161], v[206:207], 0, s[28:29]
	s_mov_b32 m0, s17
	s_nop 0
	global_load_lds_dwordx4 v[160:161], off
	s_waitcnt vmcnt(8) lgkmcnt(0)
	s_barrier
	v_mfma_f32_16x16x32_bf16 v[62:65], v[90:93], v[182:185], v[62:65]
	v_mfma_f32_16x16x32_bf16 v[58:61], v[100:103], v[182:185], v[58:61]
	v_mfma_f32_16x16x32_bf16 v[46:49], v[90:93], v[190:193], v[46:49]
	v_mfma_f32_16x16x32_bf16 v[42:45], v[100:103], v[190:193], v[42:45]
	v_mfma_f32_16x16x32_bf16 v[30:33], v[90:93], v[214:217], v[30:33]
	v_mfma_f32_16x16x32_bf16 v[26:29], v[100:103], v[214:217], v[26:29]
	v_mfma_f32_16x16x32_bf16 v[14:17], v[90:93], v[222:225], v[14:17]
	v_mfma_f32_16x16x32_bf16 v[10:13], v[100:103], v[222:225], v[10:13]
	v_mfma_f32_16x16x32_bf16 v[62:65], v[94:97], v[186:189], v[62:65]
	v_mfma_f32_16x16x32_bf16 v[58:61], v[108:111], v[186:189], v[58:61]
	v_mfma_f32_16x16x32_bf16 v[46:49], v[94:97], v[194:197], v[46:49]
	v_mfma_f32_16x16x32_bf16 v[42:45], v[108:111], v[194:197], v[42:45]
	v_mfma_f32_16x16x32_bf16 v[30:33], v[94:97], v[218:221], v[30:33]
	v_mfma_f32_16x16x32_bf16 v[26:29], v[108:111], v[218:221], v[26:29]
	v_mfma_f32_16x16x32_bf16 v[14:17], v[94:97], v[226:229], v[14:17]
	v_mfma_f32_16x16x32_bf16 v[10:13], v[108:111], v[226:229], v[10:13]
	s_setprio 0
	s_setprio 1
	v_mfma_f32_16x16x32_bf16 v[54:57], v[166:169], v[182:185], v[54:57]
	v_mfma_f32_16x16x32_bf16 v[50:53], v[174:177], v[182:185], v[50:53]
	v_mfma_f32_16x16x32_bf16 v[38:41], v[166:169], v[190:193], v[38:41]
	v_mfma_f32_16x16x32_bf16 v[34:37], v[174:177], v[190:193], v[34:37]
	v_mfma_f32_16x16x32_bf16 v[22:25], v[166:169], v[214:217], v[22:25]
	v_mfma_f32_16x16x32_bf16 v[18:21], v[174:177], v[214:217], v[18:21]
	v_mfma_f32_16x16x32_bf16 v[6:9], v[166:169], v[222:225], v[6:9]
	v_mfma_f32_16x16x32_bf16 v[2:5], v[174:177], v[222:225], v[2:5]
	v_mfma_f32_16x16x32_bf16 v[54:57], v[170:173], v[186:189], v[54:57]
	v_mfma_f32_16x16x32_bf16 v[50:53], v[178:181], v[186:189], v[50:53]
	v_mfma_f32_16x16x32_bf16 v[38:41], v[170:173], v[194:197], v[38:41]
	v_mfma_f32_16x16x32_bf16 v[34:37], v[178:181], v[194:197], v[34:37]
	v_mfma_f32_16x16x32_bf16 v[22:25], v[170:173], v[218:221], v[22:25]
	v_mfma_f32_16x16x32_bf16 v[18:21], v[178:181], v[218:221], v[18:21]
	v_mfma_f32_16x16x32_bf16 v[6:9], v[170:173], v[226:229], v[6:9]
	v_mfma_f32_16x16x32_bf16 v[2:5], v[178:181], v[226:229], v[2:5]
	s_setprio 0
	s_barrier
	s_add_i32 s66, s66, 2
	s_add_u32 s40, s40, 0x100
	s_addc_u32 s41, s41, 0
	s_add_u32 s64, s64, 0x100
	s_addc_u32 s65, s65, 0
	s_cmp_gt_u32 s66, 13
	s_cbranch_scc0 .LBB0_438
	s_and_b64 vcc, exec, s[22:23]
	s_cbranch_vccz .LBB0_441
	s_barrier

.LBB0_647:
	s_add_i32 s68, s42, 2
	s_add_u32 s43, s40, 0xfff80080
	s_addc_u32 s54, s41, -1
	s_add_i32 s70, 0, 0x10000
	s_cmp_eq_u32 s65, s42
	s_cselect_b32 s55, s49, s54
	s_cselect_b32 s54, s63, s43
	v_add_u32_e32 v146, s70, v149
	s_cselect_b32 s43, s51, s67
	s_cselect_b32 s42, s50, s66
	s_add_i32 s72, 0, 0x14000
	ds_read_b128 v[152:155], v146
	ds_read_b128 v[156:159], v146 offset:1024
	ds_read_b128 v[160:163], v146 offset:2048
	ds_read_b128 v[164:167], v146 offset:3072
	v_add_u32_e32 v146, s72, v149
	ds_read_b128 v[168:171], v146
	ds_read_b128 v[172:175], v146 offset:1024
	ds_read_b128 v[176:179], v146 offset:2048
	ds_read_b128 v[180:183], v146 offset:3072
	v_lshl_add_u64 v[146:147], s[40:41], 0, v[142:143]
	s_add_i32 m0, s11, 0xc000
	ds_read_b128 v[184:187], v150
	ds_read_b128 v[188:191], v150 offset:1024
	ds_read_b128 v[192:195], v150 offset:2048
	ds_read_b128 v[196:199], v150 offset:3072
	ds_read_b128 v[214:217], v150 offset:4096
	ds_read_b128 v[218:221], v150 offset:5120
	ds_read_b128 v[222:225], v150 offset:6144
	ds_read_b128 v[226:229], v150 offset:7168
	s_setprio 1
	global_load_lds_dwordx4 v[146:147], off
	v_lshl_add_u64 v[146:147], s[40:41], 0, v[144:145]
	s_add_i32 m0, s11, 0xe000
	s_nop 0
	global_load_lds_dwordx4 v[146:147], off
	s_waitcnt vmcnt(8) lgkmcnt(0)
	s_barrier
	v_mfma_f32_16x16x32_bf16 v[128:131], v[152:155], v[184:187], v[128:131]
	v_mfma_f32_16x16x32_bf16 v[124:127], v[160:163], v[184:187], v[124:127]
	v_mfma_f32_16x16x32_bf16 v[112:115], v[152:155], v[192:195], v[112:115]
	v_mfma_f32_16x16x32_bf16 v[108:111], v[160:163], v[192:195], v[108:111]
	v_mfma_f32_16x16x32_bf16 v[94:97], v[152:155], v[214:217], v[94:97]
	v_mfma_f32_16x16x32_bf16 v[90:93], v[160:163], v[214:217], v[90:93]
	v_mfma_f32_16x16x32_bf16 v[78:81], v[152:155], v[222:225], v[78:81]
	v_mfma_f32_16x16x32_bf16 v[74:77], v[160:163], v[222:225], v[74:77]
	v_mfma_f32_16x16x32_bf16 v[128:131], v[156:159], v[188:191], v[128:131]
	v_mfma_f32_16x16x32_bf16 v[124:127], v[164:167], v[188:191], v[124:127]
	v_mfma_f32_16x16x32_bf16 v[112:115], v[156:159], v[196:199], v[112:115]
	v_mfma_f32_16x16x32_bf16 v[108:111], v[164:167], v[196:199], v[108:111]
	v_mfma_f32_16x16x32_bf16 v[94:97], v[156:159], v[218:221], v[94:97]
	v_mfma_f32_16x16x32_bf16 v[90:93], v[164:167], v[218:221], v[90:93]
	v_mfma_f32_16x16x32_bf16 v[78:81], v[156:159], v[226:229], v[78:81]
	v_mfma_f32_16x16x32_bf16 v[74:77], v[164:167], v[226:229], v[74:77]
	s_setprio 0
	s_setprio 1
	v_mfma_f32_16x16x32_bf16 v[120:123], v[168:171], v[184:187], v[120:123]
	v_mfma_f32_16x16x32_bf16 v[116:119], v[176:179], v[184:187], v[116:119]
	v_mfma_f32_16x16x32_bf16 v[104:107], v[168:171], v[192:195], v[104:107]
	v_mfma_f32_16x16x32_bf16 v[100:103], v[176:179], v[192:195], v[100:103]
	v_mfma_f32_16x16x32_bf16 v[86:89], v[168:171], v[214:217], v[86:89]
	v_mfma_f32_16x16x32_bf16 v[82:85], v[176:179], v[214:217], v[82:85]
	v_mfma_f32_16x16x32_bf16 v[70:73], v[168:171], v[222:225], v[70:73]
	v_mfma_f32_16x16x32_bf16 v[66:69], v[176:179], v[222:225], v[66:69]
	v_mfma_f32_16x16x32_bf16 v[120:123], v[172:175], v[188:191], v[120:123]
	v_mfma_f32_16x16x32_bf16 v[116:119], v[180:183], v[188:191], v[116:119]
	v_mfma_f32_16x16x32_bf16 v[104:107], v[172:175], v[196:199], v[104:107]
	v_mfma_f32_16x16x32_bf16 v[100:103], v[180:183], v[196:199], v[100:103]
	v_mfma_f32_16x16x32_bf16 v[86:89], v[172:175], v[218:221], v[86:89]
	v_mfma_f32_16x16x32_bf16 v[82:85], v[180:183], v[218:221], v[82:85]
	v_mfma_f32_16x16x32_bf16 v[70:73], v[172:175], v[226:229], v[70:73]
	v_mfma_f32_16x16x32_bf16 v[66:69], v[180:183], v[226:229], v[66:69]
	s_barrier
	s_add_i32 s70, s70, s10
	v_lshl_add_u64 v[146:147], s[42:43], 0, v[98:99]
	s_mov_b32 m0, s70
	ds_read_b128 v[184:187], v150 offset:16384
	ds_read_b128 v[188:191], v150 offset:17408
	ds_read_b128 v[192:195], v150 offset:18432
	ds_read_b128 v[196:199], v150 offset:19456
	ds_read_b128 v[214:217], v150 offset:20480
	ds_read_b128 v[218:221], v150 offset:21504
	ds_read_b128 v[222:225], v150 offset:22528
	ds_read_b128 v[226:229], v150 offset:23552
	global_load_lds_dwordx4 v[146:147], off
	s_add_i32 m0, s70, 0x2000
	s_add_u32 s70, s42, 0x18000
	v_lshl_add_u64 v[204:205], s[42:43], 0, v[136:137]
	s_addc_u32 s71, s43, 0
	s_add_i32 s72, s72, s10
	global_load_lds_dwordx4 v[204:205], off
	v_lshl_add_u64 v[206:207], s[70:71], 0, v[98:99]
	s_mov_b32 m0, s72
	v_lshl_add_u64 v[208:209], s[54:55], 0, v[134:135]
	global_load_lds_dwordx4 v[206:207], off
	v_lshl_add_u64 v[206:207], s[70:71], 0, v[136:137]
	s_add_i32 m0, s72, 0x2000
	s_nop 0
	global_load_lds_dwordx4 v[206:207], off
	v_lshl_add_u64 v[206:207], s[54:55], 0, v[132:133]
	s_mov_b32 m0, s11
	s_nop 0
	global_load_lds_dwordx4 v[206:207], off
	s_mov_b32 m0, s12
	s_nop 0
	global_load_lds_dwordx4 v[208:209], off
	s_waitcnt vmcnt(8) lgkmcnt(0)
	s_barrier
	v_mfma_f32_16x16x32_bf16 v[62:65], v[152:155], v[184:187], v[62:65]
	v_mfma_f32_16x16x32_bf16 v[58:61], v[160:163], v[184:187], v[58:61]
	v_mfma_f32_16x16x32_bf16 v[46:49], v[152:155], v[192:195], v[46:49]
	v_mfma_f32_16x16x32_bf16 v[42:45], v[160:163], v[192:195], v[42:45]
	v_mfma_f32_16x16x32_bf16 v[30:33], v[152:155], v[214:217], v[30:33]
	v_mfma_f32_16x16x32_bf16 v[26:29], v[160:163], v[214:217], v[26:29]
	v_mfma_f32_16x16x32_bf16 v[14:17], v[152:155], v[222:225], v[14:17]
	v_mfma_f32_16x16x32_bf16 v[10:13], v[160:163], v[222:225], v[10:13]
	v_mfma_f32_16x16x32_bf16 v[62:65], v[156:159], v[188:191], v[62:65]
	v_mfma_f32_16x16x32_bf16 v[58:61], v[164:167], v[188:191], v[58:61]
	v_mfma_f32_16x16x32_bf16 v[46:49], v[156:159], v[196:199], v[46:49]
	v_mfma_f32_16x16x32_bf16 v[42:45], v[164:167], v[196:199], v[42:45]
	v_mfma_f32_16x16x32_bf16 v[30:33], v[156:159], v[218:221], v[30:33]
	v_mfma_f32_16x16x32_bf16 v[26:29], v[164:167], v[218:221], v[26:29]
	v_mfma_f32_16x16x32_bf16 v[14:17], v[156:159], v[226:229], v[14:17]
	v_mfma_f32_16x16x32_bf16 v[10:13], v[164:167], v[226:229], v[10:13]
	s_setprio 0
	s_setprio 1
	v_mfma_f32_16x16x32_bf16 v[54:57], v[168:171], v[184:187], v[54:57]
	v_mfma_f32_16x16x32_bf16 v[50:53], v[176:179], v[184:187], v[50:53]
	v_mfma_f32_16x16x32_bf16 v[38:41], v[168:171], v[192:195], v[38:41]
	v_mfma_f32_16x16x32_bf16 v[34:37], v[176:179], v[192:195], v[34:37]
	v_mfma_f32_16x16x32_bf16 v[22:25], v[168:171], v[214:217], v[22:25]
	v_mfma_f32_16x16x32_bf16 v[18:21], v[176:179], v[214:217], v[18:21]
	v_mfma_f32_16x16x32_bf16 v[6:9], v[168:171], v[222:225], v[6:9]
	v_mfma_f32_16x16x32_bf16 v[2:5], v[176:179], v[222:225], v[2:5]
	v_mfma_f32_16x16x32_bf16 v[54:57], v[172:175], v[188:191], v[54:57]
	v_mfma_f32_16x16x32_bf16 v[50:53], v[180:183], v[188:191], v[50:53]
	v_mfma_f32_16x16x32_bf16 v[38:41], v[172:175], v[196:199], v[38:41]
	v_mfma_f32_16x16x32_bf16 v[34:37], v[180:183], v[196:199], v[34:37]
	v_mfma_f32_16x16x32_bf16 v[22:25], v[172:175], v[218:221], v[22:25]
	v_mfma_f32_16x16x32_bf16 v[18:21], v[180:183], v[218:221], v[18:21]
	v_mfma_f32_16x16x32_bf16 v[6:9], v[172:175], v[226:229], v[6:9]
	v_mfma_f32_16x16x32_bf16 v[2:5], v[180:183], v[226:229], v[2:5]
	s_setprio 0
	s_barrier
	s_add_i32 s70, 0, 0x18000
	v_add_u32_e32 v151, s70, v149
	s_add_i32 s71, 0, 0x1c000
	ds_read_b128 v[152:155], v151
	ds_read_b128 v[156:159], v151 offset:1024
	ds_read_b128 v[160:163], v151 offset:2048
	ds_read_b128 v[164:167], v151 offset:3072
	v_add_u32_e32 v151, s71, v149
	ds_read_b128 v[168:171], v151
	ds_read_b128 v[172:175], v151 offset:1024
	ds_read_b128 v[176:179], v151 offset:2048
	ds_read_b128 v[180:183], v151 offset:3072
	s_add_u32 s54, s54, 0x80000
	s_addc_u32 s55, s55, 0
	s_mov_b32 m0, s13
	v_lshl_add_u64 v[210:211], s[54:55], 0, v[132:133]
	ds_read_b128 v[184:187], v150 offset:32768
	ds_read_b128 v[188:191], v150 offset:33792
	ds_read_b128 v[192:195], v150 offset:34816
	ds_read_b128 v[196:199], v150 offset:35840
	ds_read_b128 v[214:217], v150 offset:36864
	ds_read_b128 v[218:221], v150 offset:37888
	ds_read_b128 v[222:225], v150 offset:38912
	ds_read_b128 v[226:229], v150 offset:39936
	s_setprio 1
	global_load_lds_dwordx4 v[210:211], off
	v_lshl_add_u64 v[210:211], s[54:55], 0, v[134:135]
	s_mov_b32 m0, s14
	s_nop 0
	global_load_lds_dwordx4 v[210:211], off
	s_waitcnt vmcnt(8) lgkmcnt(0)
	s_barrier
	v_mfma_f32_16x16x32_bf16 v[128:131], v[152:155], v[184:187], v[128:131]
	v_mfma_f32_16x16x32_bf16 v[124:127], v[160:163], v[184:187], v[124:127]
	v_mfma_f32_16x16x32_bf16 v[112:115], v[152:155], v[192:195], v[112:115]
	v_mfma_f32_16x16x32_bf16 v[108:111], v[160:163], v[192:195], v[108:111]
	v_mfma_f32_16x16x32_bf16 v[94:97], v[152:155], v[214:217], v[94:97]
	v_mfma_f32_16x16x32_bf16 v[90:93], v[160:163], v[214:217], v[90:93]
	v_mfma_f32_16x16x32_bf16 v[78:81], v[152:155], v[222:225], v[78:81]
	v_mfma_f32_16x16x32_bf16 v[74:77], v[160:163], v[222:225], v[74:77]
	v_mfma_f32_16x16x32_bf16 v[128:131], v[156:159], v[188:191], v[128:131]
	v_mfma_f32_16x16x32_bf16 v[124:127], v[164:167], v[188:191], v[124:127]
	v_mfma_f32_16x16x32_bf16 v[112:115], v[156:159], v[196:199], v[112:115]
	v_mfma_f32_16x16x32_bf16 v[108:111], v[164:167], v[196:199], v[108:111]
	v_mfma_f32_16x16x32_bf16 v[94:97], v[156:159], v[218:221], v[94:97]
	v_mfma_f32_16x16x32_bf16 v[90:93], v[164:167], v[218:221], v[90:93]
	v_mfma_f32_16x16x32_bf16 v[78:81], v[156:159], v[226:229], v[78:81]
	v_mfma_f32_16x16x32_bf16 v[74:77], v[164:167], v[226:229], v[74:77]
	s_setprio 0
	s_setprio 1
	v_mfma_f32_16x16x32_bf16 v[120:123], v[168:171], v[184:187], v[120:123]
	v_mfma_f32_16x16x32_bf16 v[116:119], v[176:179], v[184:187], v[116:119]
	v_mfma_f32_16x16x32_bf16 v[104:107], v[168:171], v[192:195], v[104:107]
	v_mfma_f32_16x16x32_bf16 v[100:103], v[176:179], v[192:195], v[100:103]
	v_mfma_f32_16x16x32_bf16 v[86:89], v[168:171], v[214:217], v[86:89]
	v_mfma_f32_16x16x32_bf16 v[82:85], v[176:179], v[214:217], v[82:85]
	v_mfma_f32_16x16x32_bf16 v[70:73], v[168:171], v[222:225], v[70:73]
	v_mfma_f32_16x16x32_bf16 v[66:69], v[176:179], v[222:225], v[66:69]
	v_mfma_f32_16x16x32_bf16 v[120:123], v[172:175], v[188:191], v[120:123]
	v_mfma_f32_16x16x32_bf16 v[116:119], v[180:183], v[188:191], v[116:119]
	v_mfma_f32_16x16x32_bf16 v[104:107], v[172:175], v[196:199], v[104:107]
	v_mfma_f32_16x16x32_bf16 v[100:103], v[180:183], v[196:199], v[100:103]
	v_mfma_f32_16x16x32_bf16 v[86:89], v[172:175], v[218:221], v[86:89]
	v_mfma_f32_16x16x32_bf16 v[82:85], v[180:183], v[218:221], v[82:85]
	v_mfma_f32_16x16x32_bf16 v[70:73], v[172:175], v[226:229], v[70:73]
	v_mfma_f32_16x16x32_bf16 v[66:69], v[180:183], v[226:229], v[66:69]
	s_barrier
	s_add_i32 s54, s70, s10
	v_lshl_add_u64 v[146:147], v[146:147], 0, s[28:29]
	s_mov_b32 m0, s54
	ds_read_b128 v[184:187], v150 offset:49152
	ds_read_b128 v[188:191], v150 offset:50176
	ds_read_b128 v[192:195], v150 offset:51200
	ds_read_b128 v[196:199], v150 offset:52224
	ds_read_b128 v[214:217], v150 offset:53248
	ds_read_b128 v[218:221], v150 offset:54272
	ds_read_b128 v[222:225], v150 offset:55296
	ds_read_b128 v[226:229], v150 offset:56320
	global_load_lds_dwordx4 v[146:147], off
	s_add_i32 m0, s54, 0x2000
	s_add_u32 s42, s42, 0x18080
	v_lshl_add_u64 v[146:147], v[204:205], 0, s[28:29]
	s_addc_u32 s43, s43, 0
	s_add_i32 s54, s71, s10
	global_load_lds_dwordx4 v[146:147], off
	v_lshl_add_u64 v[146:147], s[42:43], 0, v[98:99]
	s_mov_b32 m0, s54
	s_nop 0
	global_load_lds_dwordx4 v[146:147], off
	v_lshl_add_u64 v[146:147], s[42:43], 0, v[136:137]
	s_add_i32 m0, s54, 0x2000
	s_nop 0
	global_load_lds_dwordx4 v[146:147], off
	v_lshl_add_u64 v[146:147], v[206:207], 0, s[28:29]
	s_mov_b32 m0, s17
	s_nop 0
	global_load_lds_dwordx4 v[146:147], off
	v_lshl_add_u64 v[146:147], v[208:209], 0, s[28:29]
	s_mov_b32 m0, s18
	s_nop 0
	global_load_lds_dwordx4 v[146:147], off
	s_waitcnt vmcnt(8) lgkmcnt(0)
	s_barrier
	v_mfma_f32_16x16x32_bf16 v[62:65], v[152:155], v[184:187], v[62:65]
	v_mfma_f32_16x16x32_bf16 v[58:61], v[160:163], v[184:187], v[58:61]
	v_mfma_f32_16x16x32_bf16 v[46:49], v[152:155], v[192:195], v[46:49]
	v_mfma_f32_16x16x32_bf16 v[42:45], v[160:163], v[192:195], v[42:45]
	v_mfma_f32_16x16x32_bf16 v[30:33], v[152:155], v[214:217], v[30:33]
	v_mfma_f32_16x16x32_bf16 v[26:29], v[160:163], v[214:217], v[26:29]
	v_mfma_f32_16x16x32_bf16 v[14:17], v[152:155], v[222:225], v[14:17]
	v_mfma_f32_16x16x32_bf16 v[10:13], v[160:163], v[222:225], v[10:13]
	v_mfma_f32_16x16x32_bf16 v[62:65], v[156:159], v[188:191], v[62:65]
	v_mfma_f32_16x16x32_bf16 v[58:61], v[164:167], v[188:191], v[58:61]
	v_mfma_f32_16x16x32_bf16 v[46:49], v[156:159], v[196:199], v[46:49]
	v_mfma_f32_16x16x32_bf16 v[42:45], v[164:167], v[196:199], v[42:45]
	v_mfma_f32_16x16x32_bf16 v[30:33], v[156:159], v[218:221], v[30:33]
	v_mfma_f32_16x16x32_bf16 v[26:29], v[164:167], v[218:221], v[26:29]
	v_mfma_f32_16x16x32_bf16 v[14:17], v[156:159], v[226:229], v[14:17]
	v_mfma_f32_16x16x32_bf16 v[10:13], v[164:167], v[226:229], v[10:13]
	s_setprio 0
	s_setprio 1
	v_mfma_f32_16x16x32_bf16 v[54:57], v[168:171], v[184:187], v[54:57]
	v_mfma_f32_16x16x32_bf16 v[50:53], v[176:179], v[184:187], v[50:53]
	v_mfma_f32_16x16x32_bf16 v[38:41], v[168:171], v[192:195], v[38:41]
	v_mfma_f32_16x16x32_bf16 v[34:37], v[176:179], v[192:195], v[34:37]
	v_mfma_f32_16x16x32_bf16 v[22:25], v[168:171], v[214:217], v[22:25]
	v_mfma_f32_16x16x32_bf16 v[18:21], v[176:179], v[214:217], v[18:21]
	v_mfma_f32_16x16x32_bf16 v[6:9], v[168:171], v[222:225], v[6:9]
	v_mfma_f32_16x16x32_bf16 v[2:5], v[176:179], v[222:225], v[2:5]
	v_mfma_f32_16x16x32_bf16 v[54:57], v[172:175], v[188:191], v[54:57]
	v_mfma_f32_16x16x32_bf16 v[50:53], v[180:183], v[188:191], v[50:53]
	v_mfma_f32_16x16x32_bf16 v[38:41], v[172:175], v[196:199], v[38:41]
	v_mfma_f32_16x16x32_bf16 v[34:37], v[180:183], v[196:199], v[34:37]
	v_mfma_f32_16x16x32_bf16 v[22:25], v[172:175], v[218:221], v[22:25]
	v_mfma_f32_16x16x32_bf16 v[18:21], v[180:183], v[218:221], v[18:21]
	v_mfma_f32_16x16x32_bf16 v[6:9], v[172:175], v[226:229], v[6:9]
	v_mfma_f32_16x16x32_bf16 v[2:5], v[180:183], v[226:229], v[2:5]
	s_setprio 0
	s_barrier
	s_add_u32 s40, s40, 0x100
	s_addc_u32 s41, s41, 0
	s_add_u32 s66, s66, 0x100
	s_addc_u32 s67, s67, 0
	s_cmp_ge_i32 s68, s62
	s_mov_b32 s42, s68
	s_cbranch_scc0 .LBB0_647
	s_and_b64 vcc, exec, s[44:45]
	s_cbranch_vccz .LBB0_650
	s_barrier

.LBB0_893:
	s_add_u32 s50, s48, 0xfffe0080
	s_addc_u32 s51, s49, -1
	s_add_i32 s57, 0, 0x10000
	s_cmp_eq_u32 s56, 4
	s_cselect_b32 s53, s19, s51
	s_cselect_b32 s52, s33, s50
	v_add_u32_e32 v98, s57, v144
	s_cselect_b32 s51, s37, s55
	s_cselect_b32 s50, s39, s54
	s_add_i32 s60, 0, 0x14000
	ds_read_b128 v[146:149], v98
	ds_read_b128 v[150:153], v98 offset:1024
	ds_read_b128 v[154:157], v98 offset:2048
	ds_read_b128 v[158:161], v98 offset:3072
	v_add_u32_e32 v98, s60, v144
	ds_read_b128 v[162:165], v98
	ds_read_b128 v[166:169], v98 offset:1024
	ds_read_b128 v[170:173], v98 offset:2048
	ds_read_b128 v[174:177], v98 offset:3072
	v_lshl_add_u64 v[198:199], s[48:49], 0, v[140:141]
	s_add_i32 m0, s4, 0xc000
	ds_read_b128 v[178:181], v145
	ds_read_b128 v[182:185], v145 offset:1024
	ds_read_b128 v[186:189], v145 offset:2048
	ds_read_b128 v[190:193], v145 offset:3072
	ds_read_b128 v[194:197], v145 offset:4096
	ds_read_b128 v[204:207], v145 offset:5120
	ds_read_b128 v[208:211], v145 offset:6144
	ds_read_b128 v[214:217], v145 offset:7168
	s_setprio 1
	global_load_lds_dwordx4 v[198:199], off
	v_lshl_add_u64 v[198:199], s[48:49], 0, v[142:143]
	s_add_i32 m0, s4, 0xe000
	s_nop 0
	global_load_lds_dwordx4 v[198:199], off
	s_waitcnt vmcnt(8) lgkmcnt(0)
	s_barrier
	v_mfma_f32_16x16x32_bf16 v[128:131], v[146:149], v[178:181], v[128:131]
	v_mfma_f32_16x16x32_bf16 v[124:127], v[154:157], v[178:181], v[124:127]
	v_mfma_f32_16x16x32_bf16 v[112:115], v[146:149], v[186:189], v[112:115]
	v_mfma_f32_16x16x32_bf16 v[108:111], v[154:157], v[186:189], v[108:111]
	v_mfma_f32_16x16x32_bf16 v[94:97], v[146:149], v[194:197], v[94:97]
	v_mfma_f32_16x16x32_bf16 v[90:93], v[154:157], v[194:197], v[90:93]
	v_mfma_f32_16x16x32_bf16 v[78:81], v[146:149], v[208:211], v[78:81]
	v_mfma_f32_16x16x32_bf16 v[74:77], v[154:157], v[208:211], v[74:77]
	v_mfma_f32_16x16x32_bf16 v[128:131], v[150:153], v[182:185], v[128:131]
	v_mfma_f32_16x16x32_bf16 v[124:127], v[158:161], v[182:185], v[124:127]
	v_mfma_f32_16x16x32_bf16 v[112:115], v[150:153], v[190:193], v[112:115]
	v_mfma_f32_16x16x32_bf16 v[108:111], v[158:161], v[190:193], v[108:111]
	v_mfma_f32_16x16x32_bf16 v[94:97], v[150:153], v[204:207], v[94:97]
	v_mfma_f32_16x16x32_bf16 v[90:93], v[158:161], v[204:207], v[90:93]
	v_mfma_f32_16x16x32_bf16 v[78:81], v[150:153], v[214:217], v[78:81]
	v_mfma_f32_16x16x32_bf16 v[74:77], v[158:161], v[214:217], v[74:77]
	s_setprio 0
	s_setprio 1
	v_mfma_f32_16x16x32_bf16 v[120:123], v[162:165], v[178:181], v[120:123]
	v_mfma_f32_16x16x32_bf16 v[116:119], v[170:173], v[178:181], v[116:119]
	v_mfma_f32_16x16x32_bf16 v[104:107], v[162:165], v[186:189], v[104:107]
	v_mfma_f32_16x16x32_bf16 v[100:103], v[170:173], v[186:189], v[100:103]
	v_mfma_f32_16x16x32_bf16 v[86:89], v[162:165], v[194:197], v[86:89]
	v_mfma_f32_16x16x32_bf16 v[82:85], v[170:173], v[194:197], v[82:85]
	v_mfma_f32_16x16x32_bf16 v[70:73], v[162:165], v[208:211], v[70:73]
	v_mfma_f32_16x16x32_bf16 v[66:69], v[170:173], v[208:211], v[66:69]
	v_mfma_f32_16x16x32_bf16 v[120:123], v[166:169], v[182:185], v[120:123]
	v_mfma_f32_16x16x32_bf16 v[116:119], v[174:177], v[182:185], v[116:119]
	v_mfma_f32_16x16x32_bf16 v[104:107], v[166:169], v[190:193], v[104:107]
	v_mfma_f32_16x16x32_bf16 v[100:103], v[174:177], v[190:193], v[100:103]
	v_mfma_f32_16x16x32_bf16 v[86:89], v[166:169], v[204:207], v[86:89]
	v_mfma_f32_16x16x32_bf16 v[82:85], v[174:177], v[204:207], v[82:85]
	v_mfma_f32_16x16x32_bf16 v[70:73], v[166:169], v[214:217], v[70:73]
	v_mfma_f32_16x16x32_bf16 v[66:69], v[174:177], v[214:217], v[66:69]
	s_barrier
	s_add_i32 s57, s57, s2
	v_lshl_add_u64 v[198:199], s[50:51], 0, v[136:137]
	s_mov_b32 m0, s57
	ds_read_b128 v[178:181], v145 offset:16384
	ds_read_b128 v[182:185], v145 offset:17408
	ds_read_b128 v[186:189], v145 offset:18432
	ds_read_b128 v[190:193], v145 offset:19456
	ds_read_b128 v[194:197], v145 offset:20480
	ds_read_b128 v[204:207], v145 offset:21504
	ds_read_b128 v[208:211], v145 offset:22528
	ds_read_b128 v[214:217], v145 offset:23552
	global_load_lds_dwordx4 v[198:199], off
	s_add_i32 m0, s57, 0x2000
	s_add_u32 s58, s50, 0x20000
	v_lshl_add_u64 v[218:219], s[50:51], 0, v[132:133]
	s_addc_u32 s59, s51, 0
	s_add_i32 s57, s60, s2
	global_load_lds_dwordx4 v[218:219], off
	v_lshl_add_u64 v[220:221], s[58:59], 0, v[136:137]
	s_mov_b32 m0, s57
	v_lshl_add_u64 v[222:223], s[52:53], 0, v[134:135]
	global_load_lds_dwordx4 v[220:221], off
	v_lshl_add_u64 v[220:221], s[58:59], 0, v[132:133]
	s_add_i32 m0, s57, 0x2000
	s_nop 0
	global_load_lds_dwordx4 v[220:221], off
	v_lshl_add_u64 v[220:221], s[52:53], 0, v[138:139]
	s_mov_b32 m0, s4
	s_nop 0
	global_load_lds_dwordx4 v[220:221], off
	s_mov_b32 m0, s7
	s_nop 0
	global_load_lds_dwordx4 v[222:223], off
	s_waitcnt vmcnt(8) lgkmcnt(0)
	s_barrier
	v_mfma_f32_16x16x32_bf16 v[62:65], v[146:149], v[178:181], v[62:65]
	v_mfma_f32_16x16x32_bf16 v[58:61], v[154:157], v[178:181], v[58:61]
	v_mfma_f32_16x16x32_bf16 v[46:49], v[146:149], v[186:189], v[46:49]
	v_mfma_f32_16x16x32_bf16 v[42:45], v[154:157], v[186:189], v[42:45]
	v_mfma_f32_16x16x32_bf16 v[30:33], v[146:149], v[194:197], v[30:33]
	v_mfma_f32_16x16x32_bf16 v[26:29], v[154:157], v[194:197], v[26:29]
	v_mfma_f32_16x16x32_bf16 v[14:17], v[146:149], v[208:211], v[14:17]
	v_mfma_f32_16x16x32_bf16 v[10:13], v[154:157], v[208:211], v[10:13]
	v_mfma_f32_16x16x32_bf16 v[62:65], v[150:153], v[182:185], v[62:65]
	v_mfma_f32_16x16x32_bf16 v[58:61], v[158:161], v[182:185], v[58:61]
	v_mfma_f32_16x16x32_bf16 v[46:49], v[150:153], v[190:193], v[46:49]
	v_mfma_f32_16x16x32_bf16 v[42:45], v[158:161], v[190:193], v[42:45]
	v_mfma_f32_16x16x32_bf16 v[30:33], v[150:153], v[204:207], v[30:33]
	v_mfma_f32_16x16x32_bf16 v[26:29], v[158:161], v[204:207], v[26:29]
	v_mfma_f32_16x16x32_bf16 v[14:17], v[150:153], v[214:217], v[14:17]
	v_mfma_f32_16x16x32_bf16 v[10:13], v[158:161], v[214:217], v[10:13]
	s_setprio 0
	s_setprio 1
	v_mfma_f32_16x16x32_bf16 v[54:57], v[162:165], v[178:181], v[54:57]
	v_mfma_f32_16x16x32_bf16 v[50:53], v[170:173], v[178:181], v[50:53]
	v_mfma_f32_16x16x32_bf16 v[38:41], v[162:165], v[186:189], v[38:41]
	v_mfma_f32_16x16x32_bf16 v[34:37], v[170:173], v[186:189], v[34:37]
	v_mfma_f32_16x16x32_bf16 v[22:25], v[162:165], v[194:197], v[22:25]
	v_mfma_f32_16x16x32_bf16 v[18:21], v[170:173], v[194:197], v[18:21]
	v_mfma_f32_16x16x32_bf16 v[6:9], v[162:165], v[208:211], v[6:9]
	v_mfma_f32_16x16x32_bf16 v[2:5], v[170:173], v[208:211], v[2:5]
	v_mfma_f32_16x16x32_bf16 v[54:57], v[166:169], v[182:185], v[54:57]
	v_mfma_f32_16x16x32_bf16 v[50:53], v[174:177], v[182:185], v[50:53]
	v_mfma_f32_16x16x32_bf16 v[38:41], v[166:169], v[190:193], v[38:41]
	v_mfma_f32_16x16x32_bf16 v[34:37], v[174:177], v[190:193], v[34:37]
	v_mfma_f32_16x16x32_bf16 v[22:25], v[166:169], v[204:207], v[22:25]
	v_mfma_f32_16x16x32_bf16 v[18:21], v[174:177], v[204:207], v[18:21]
	v_mfma_f32_16x16x32_bf16 v[6:9], v[166:169], v[214:217], v[6:9]
	v_mfma_f32_16x16x32_bf16 v[2:5], v[174:177], v[214:217], v[2:5]
	s_setprio 0
	s_barrier
	s_add_i32 s57, 0, 0x18000
	v_add_u32_e32 v98, s57, v144
	s_add_i32 s58, 0, 0x1c000
	ds_read_b128 v[146:149], v98
	ds_read_b128 v[150:153], v98 offset:1024
	ds_read_b128 v[154:157], v98 offset:2048
	ds_read_b128 v[158:161], v98 offset:3072
	v_add_u32_e32 v98, s58, v144
	ds_read_b128 v[162:165], v98
	ds_read_b128 v[166:169], v98 offset:1024
	ds_read_b128 v[170:173], v98 offset:2048
	ds_read_b128 v[174:177], v98 offset:3072
	s_add_u32 s52, s52, 0x20000
	s_addc_u32 s53, s53, 0
	s_mov_b32 m0, s8
	v_lshl_add_u64 v[224:225], s[52:53], 0, v[138:139]
	ds_read_b128 v[178:181], v145 offset:32768
	ds_read_b128 v[182:185], v145 offset:33792
	ds_read_b128 v[186:189], v145 offset:34816
	ds_read_b128 v[190:193], v145 offset:35840
	ds_read_b128 v[194:197], v145 offset:36864
	ds_read_b128 v[204:207], v145 offset:37888
	ds_read_b128 v[208:211], v145 offset:38912
	ds_read_b128 v[214:217], v145 offset:39936
	s_setprio 1
	global_load_lds_dwordx4 v[224:225], off
	v_lshl_add_u64 v[224:225], s[52:53], 0, v[134:135]
	s_mov_b32 m0, s9
	s_nop 0
	global_load_lds_dwordx4 v[224:225], off
	s_waitcnt vmcnt(8) lgkmcnt(0)
	s_barrier
	v_mfma_f32_16x16x32_bf16 v[128:131], v[146:149], v[178:181], v[128:131]
	v_mfma_f32_16x16x32_bf16 v[124:127], v[154:157], v[178:181], v[124:127]
	v_mfma_f32_16x16x32_bf16 v[112:115], v[146:149], v[186:189], v[112:115]
	v_mfma_f32_16x16x32_bf16 v[108:111], v[154:157], v[186:189], v[108:111]
	v_mfma_f32_16x16x32_bf16 v[94:97], v[146:149], v[194:197], v[94:97]
	v_mfma_f32_16x16x32_bf16 v[90:93], v[154:157], v[194:197], v[90:93]
	v_mfma_f32_16x16x32_bf16 v[78:81], v[146:149], v[208:211], v[78:81]
	v_mfma_f32_16x16x32_bf16 v[74:77], v[154:157], v[208:211], v[74:77]
	v_mfma_f32_16x16x32_bf16 v[128:131], v[150:153], v[182:185], v[128:131]
	v_mfma_f32_16x16x32_bf16 v[124:127], v[158:161], v[182:185], v[124:127]
	v_mfma_f32_16x16x32_bf16 v[112:115], v[150:153], v[190:193], v[112:115]
	v_mfma_f32_16x16x32_bf16 v[108:111], v[158:161], v[190:193], v[108:111]
	v_mfma_f32_16x16x32_bf16 v[94:97], v[150:153], v[204:207], v[94:97]
	v_mfma_f32_16x16x32_bf16 v[90:93], v[158:161], v[204:207], v[90:93]
	v_mfma_f32_16x16x32_bf16 v[78:81], v[150:153], v[214:217], v[78:81]
	v_mfma_f32_16x16x32_bf16 v[74:77], v[158:161], v[214:217], v[74:77]
	s_setprio 0
	s_setprio 1
	v_mfma_f32_16x16x32_bf16 v[120:123], v[162:165], v[178:181], v[120:123]
	v_mfma_f32_16x16x32_bf16 v[116:119], v[170:173], v[178:181], v[116:119]
	v_mfma_f32_16x16x32_bf16 v[104:107], v[162:165], v[186:189], v[104:107]
	v_mfma_f32_16x16x32_bf16 v[100:103], v[170:173], v[186:189], v[100:103]
	v_mfma_f32_16x16x32_bf16 v[86:89], v[162:165], v[194:197], v[86:89]
	v_mfma_f32_16x16x32_bf16 v[82:85], v[170:173], v[194:197], v[82:85]
	v_mfma_f32_16x16x32_bf16 v[70:73], v[162:165], v[208:211], v[70:73]
	v_mfma_f32_16x16x32_bf16 v[66:69], v[170:173], v[208:211], v[66:69]
	v_mfma_f32_16x16x32_bf16 v[120:123], v[166:169], v[182:185], v[120:123]
	v_mfma_f32_16x16x32_bf16 v[116:119], v[174:177], v[182:185], v[116:119]
	v_mfma_f32_16x16x32_bf16 v[104:107], v[166:169], v[190:193], v[104:107]
	v_mfma_f32_16x16x32_bf16 v[100:103], v[174:177], v[190:193], v[100:103]
	v_mfma_f32_16x16x32_bf16 v[86:89], v[166:169], v[204:207], v[86:89]
	v_mfma_f32_16x16x32_bf16 v[82:85], v[174:177], v[204:207], v[82:85]
	v_mfma_f32_16x16x32_bf16 v[70:73], v[166:169], v[214:217], v[70:73]
	v_mfma_f32_16x16x32_bf16 v[66:69], v[174:177], v[214:217], v[66:69]
	s_barrier
	s_add_i32 s52, s57, s2
	v_lshl_add_u64 v[198:199], v[198:199], 0, s[28:29]
	s_mov_b32 m0, s52
	ds_read_b128 v[178:181], v145 offset:49152
	ds_read_b128 v[182:185], v145 offset:50176
	ds_read_b128 v[186:189], v145 offset:51200
	ds_read_b128 v[190:193], v145 offset:52224
	ds_read_b128 v[194:197], v145 offset:53248
	ds_read_b128 v[204:207], v145 offset:54272
	ds_read_b128 v[208:211], v145 offset:55296
	ds_read_b128 v[214:217], v145 offset:56320
	global_load_lds_dwordx4 v[198:199], off
	s_add_i32 m0, s52, 0x2000
	s_add_u32 s50, s50, 0x20080
	v_lshl_add_u64 v[198:199], v[218:219], 0, s[28:29]
	s_addc_u32 s51, s51, 0
	s_add_i32 s52, s58, s2
	global_load_lds_dwordx4 v[198:199], off
	v_lshl_add_u64 v[198:199], s[50:51], 0, v[136:137]
	s_mov_b32 m0, s52
	s_nop 0
	global_load_lds_dwordx4 v[198:199], off
	v_lshl_add_u64 v[198:199], s[50:51], 0, v[132:133]
	s_add_i32 m0, s52, 0x2000
	s_nop 0
	global_load_lds_dwordx4 v[198:199], off
	v_lshl_add_u64 v[198:199], v[220:221], 0, s[28:29]
	s_mov_b32 m0, s12
	s_nop 0
	global_load_lds_dwordx4 v[198:199], off
	v_lshl_add_u64 v[198:199], v[222:223], 0, s[28:29]
	s_mov_b32 m0, s13
	s_nop 0
	global_load_lds_dwordx4 v[198:199], off
	s_waitcnt vmcnt(8) lgkmcnt(0)
	s_barrier
	v_mfma_f32_16x16x32_bf16 v[62:65], v[146:149], v[178:181], v[62:65]
	v_mfma_f32_16x16x32_bf16 v[58:61], v[154:157], v[178:181], v[58:61]
	v_mfma_f32_16x16x32_bf16 v[46:49], v[146:149], v[186:189], v[46:49]
	v_mfma_f32_16x16x32_bf16 v[42:45], v[154:157], v[186:189], v[42:45]
	v_mfma_f32_16x16x32_bf16 v[30:33], v[146:149], v[194:197], v[30:33]
	v_mfma_f32_16x16x32_bf16 v[26:29], v[154:157], v[194:197], v[26:29]
	v_mfma_f32_16x16x32_bf16 v[14:17], v[146:149], v[208:211], v[14:17]
	v_mfma_f32_16x16x32_bf16 v[10:13], v[154:157], v[208:211], v[10:13]
	v_mfma_f32_16x16x32_bf16 v[62:65], v[150:153], v[182:185], v[62:65]
	v_mfma_f32_16x16x32_bf16 v[58:61], v[158:161], v[182:185], v[58:61]
	v_mfma_f32_16x16x32_bf16 v[46:49], v[150:153], v[190:193], v[46:49]
	v_mfma_f32_16x16x32_bf16 v[42:45], v[158:161], v[190:193], v[42:45]
	v_mfma_f32_16x16x32_bf16 v[30:33], v[150:153], v[204:207], v[30:33]
	v_mfma_f32_16x16x32_bf16 v[26:29], v[158:161], v[204:207], v[26:29]
	v_mfma_f32_16x16x32_bf16 v[14:17], v[150:153], v[214:217], v[14:17]
	v_mfma_f32_16x16x32_bf16 v[10:13], v[158:161], v[214:217], v[10:13]
	s_setprio 0
	s_setprio 1
	v_mfma_f32_16x16x32_bf16 v[54:57], v[162:165], v[178:181], v[54:57]
	v_mfma_f32_16x16x32_bf16 v[50:53], v[170:173], v[178:181], v[50:53]
	v_mfma_f32_16x16x32_bf16 v[38:41], v[162:165], v[186:189], v[38:41]
	v_mfma_f32_16x16x32_bf16 v[34:37], v[170:173], v[186:189], v[34:37]
	v_mfma_f32_16x16x32_bf16 v[22:25], v[162:165], v[194:197], v[22:25]
	v_mfma_f32_16x16x32_bf16 v[18:21], v[170:173], v[194:197], v[18:21]
	v_mfma_f32_16x16x32_bf16 v[6:9], v[162:165], v[208:211], v[6:9]
	v_mfma_f32_16x16x32_bf16 v[2:5], v[170:173], v[208:211], v[2:5]
	v_mfma_f32_16x16x32_bf16 v[54:57], v[166:169], v[182:185], v[54:57]
	v_mfma_f32_16x16x32_bf16 v[50:53], v[174:177], v[182:185], v[50:53]
	v_mfma_f32_16x16x32_bf16 v[38:41], v[166:169], v[190:193], v[38:41]
	v_mfma_f32_16x16x32_bf16 v[34:37], v[174:177], v[190:193], v[34:37]
	v_mfma_f32_16x16x32_bf16 v[22:25], v[166:169], v[204:207], v[22:25]
	v_mfma_f32_16x16x32_bf16 v[18:21], v[174:177], v[204:207], v[18:21]
	v_mfma_f32_16x16x32_bf16 v[6:9], v[166:169], v[214:217], v[6:9]
	v_mfma_f32_16x16x32_bf16 v[2:5], v[174:177], v[214:217], v[2:5]
	s_setprio 0
	s_barrier
	s_add_i32 s56, s56, 2
	s_add_u32 s48, s48, 0x100
	s_addc_u32 s49, s49, 0
	s_add_u32 s54, s54, 0x100
	s_addc_u32 s55, s55, 0
	s_cmp_gt_u32 s56, 5
	s_cbranch_scc0 .LBB0_893
	s_and_b64 vcc, exec, s[22:23]
	s_cbranch_vccz .LBB0_896
	s_barrier

.LBB0_1072:
	s_add_u32 s60, s56, s58
	s_addc_u32 s61, s57, s59
	s_add_u32 s60, s60, 0x100
	s_addc_u32 s61, s61, 0
	s_add_u32 s71, s66, s58
	s_addc_u32 s72, s67, s59
	s_add_i32 s73, 0, 0x10000
	s_cmpk_eq_i32 s58, 0x700
	s_cselect_b32 s63, s45, s61
	s_cselect_b32 s62, s51, s60
	v_add_u32_e32 v98, s73, v214
	s_cselect_b32 s61, s49, s72
	s_cselect_b32 s60, s65, s71
	s_add_i32 s71, 0, 0x14000
	ds_read_b128 v[138:141], v98
	ds_read_b128 v[142:145], v98 offset:1024
	ds_read_b128 v[146:149], v98 offset:2048
	ds_read_b128 v[150:153], v98 offset:3072
	v_add_u32_e32 v98, s71, v214
	ds_read_b128 v[154:157], v98
	ds_read_b128 v[158:161], v98 offset:1024
	ds_read_b128 v[162:165], v98 offset:2048
	ds_read_b128 v[166:169], v98 offset:3072
	v_lshl_add_u64 v[100:101], v[134:135], 0, s[58:59]
	s_add_i32 m0, s9, 0xc000
	ds_read_b128 v[170:173], v218
	ds_read_b128 v[186:189], v218 offset:1024
	ds_read_b128 v[190:193], v218 offset:2048
	ds_read_b128 v[194:197], v218 offset:3072
	ds_read_b128 v[204:207], v218 offset:4096
	ds_read_b128 v[208:211], v218 offset:5120
	ds_read_b128 v[220:223], v218 offset:6144
	ds_read_b128 v[224:227], v218 offset:7168
	s_setprio 1
	global_load_lds_dwordx4 v[100:101], off
	v_lshl_add_u64 v[100:101], v[136:137], 0, s[58:59]
	s_add_i32 m0, s9, 0xe000
	s_nop 0
	global_load_lds_dwordx4 v[100:101], off
	s_waitcnt vmcnt(8) lgkmcnt(0)
	s_barrier
	v_mfma_f32_16x16x32_bf16 v[130:133], v[138:141], v[170:173], v[130:133]
	v_mfma_f32_16x16x32_bf16 v[126:129], v[146:149], v[170:173], v[126:129]
	v_mfma_f32_16x16x32_bf16 v[122:125], v[138:141], v[190:193], v[122:125]
	v_mfma_f32_16x16x32_bf16 v[118:121], v[146:149], v[190:193], v[118:121]
	v_mfma_f32_16x16x32_bf16 v[114:117], v[138:141], v[204:207], v[114:117]
	v_mfma_f32_16x16x32_bf16 v[110:113], v[146:149], v[204:207], v[110:113]
	v_mfma_f32_16x16x32_bf16 v[106:109], v[138:141], v[220:223], v[106:109]
	v_mfma_f32_16x16x32_bf16 v[100:103], v[146:149], v[220:223], v[102:105]
	v_mfma_f32_16x16x32_bf16 v[130:133], v[142:145], v[186:189], v[130:133]
	v_mfma_f32_16x16x32_bf16 v[126:129], v[150:153], v[186:189], v[126:129]
	v_mfma_f32_16x16x32_bf16 v[122:125], v[142:145], v[194:197], v[122:125]
	v_mfma_f32_16x16x32_bf16 v[118:121], v[150:153], v[194:197], v[118:121]
	v_mfma_f32_16x16x32_bf16 v[114:117], v[142:145], v[208:211], v[114:117]
	v_mfma_f32_16x16x32_bf16 v[110:113], v[150:153], v[208:211], v[110:113]
	v_mfma_f32_16x16x32_bf16 v[106:109], v[142:145], v[224:227], v[106:109]
	v_mfma_f32_16x16x32_bf16 v[100:103], v[150:153], v[224:227], v[100:103]
	s_setprio 0
	s_setprio 1
	v_mfma_f32_16x16x32_bf16 v[62:65], v[154:157], v[170:173], v[62:65]
	v_mfma_f32_16x16x32_bf16 v[58:61], v[162:165], v[170:173], v[58:61]
	v_mfma_f32_16x16x32_bf16 v[54:57], v[154:157], v[190:193], v[54:57]
	v_mfma_f32_16x16x32_bf16 v[50:53], v[162:165], v[190:193], v[50:53]
	v_mfma_f32_16x16x32_bf16 v[46:49], v[154:157], v[204:207], v[46:49]
	v_mfma_f32_16x16x32_bf16 v[42:45], v[162:165], v[204:207], v[42:45]
	v_mfma_f32_16x16x32_bf16 v[38:41], v[154:157], v[220:223], v[38:41]
	v_mfma_f32_16x16x32_bf16 v[34:37], v[162:165], v[220:223], v[34:37]
	v_mfma_f32_16x16x32_bf16 v[62:65], v[158:161], v[186:189], v[62:65]
	v_mfma_f32_16x16x32_bf16 v[58:61], v[166:169], v[186:189], v[58:61]
	v_mfma_f32_16x16x32_bf16 v[54:57], v[158:161], v[194:197], v[54:57]
	v_mfma_f32_16x16x32_bf16 v[50:53], v[166:169], v[194:197], v[50:53]
	v_mfma_f32_16x16x32_bf16 v[46:49], v[158:161], v[208:211], v[46:49]
	v_mfma_f32_16x16x32_bf16 v[42:45], v[166:169], v[208:211], v[42:45]
	v_mfma_f32_16x16x32_bf16 v[38:41], v[158:161], v[224:227], v[38:41]
	v_mfma_f32_16x16x32_bf16 v[34:37], v[166:169], v[224:227], v[34:37]
	s_barrier
	s_add_i32 s72, s73, s4
	v_lshl_add_u64 v[198:199], s[60:61], 0, v[176:177]
	s_mov_b32 m0, s72
	ds_read_b128 v[170:173], v218 offset:16384
	ds_read_b128 v[186:189], v218 offset:17408
	ds_read_b128 v[190:193], v218 offset:18432
	ds_read_b128 v[194:197], v218 offset:19456
	ds_read_b128 v[204:207], v218 offset:20480
	ds_read_b128 v[208:211], v218 offset:21504
	ds_read_b128 v[220:223], v218 offset:22528
	ds_read_b128 v[224:227], v218 offset:23552
	global_load_lds_dwordx4 v[198:199], off
	s_add_i32 m0, s72, 0x2000
	s_add_u32 s72, s60, 0x40000
	v_lshl_add_u64 v[228:229], s[60:61], 0, v[180:181]
	s_addc_u32 s73, s61, 0
	s_add_i32 s71, s71, s4
	global_load_lds_dwordx4 v[228:229], off
	v_lshl_add_u64 v[104:105], s[72:73], 0, v[176:177]
	s_mov_b32 m0, s71
	v_lshl_add_u64 v[230:231], s[62:63], 0, v[174:175]
	global_load_lds_dwordx4 v[104:105], off
	v_lshl_add_u64 v[104:105], s[72:73], 0, v[180:181]
	s_add_i32 m0, s71, 0x2000
	v_lshl_add_u64 v[232:233], s[62:63], 0, v[178:179]
	global_load_lds_dwordx4 v[104:105], off
	s_mov_b32 m0, s9
	s_nop 0
	global_load_lds_dwordx4 v[230:231], off
	s_mov_b32 m0, s10
	s_nop 0
	global_load_lds_dwordx4 v[232:233], off
	s_waitcnt vmcnt(8) lgkmcnt(0)
	s_barrier
	v_mfma_f32_16x16x32_bf16 v[94:97], v[138:141], v[170:173], v[94:97]
	v_mfma_f32_16x16x32_bf16 v[90:93], v[146:149], v[170:173], v[90:93]
	v_mfma_f32_16x16x32_bf16 v[86:89], v[138:141], v[190:193], v[86:89]
	v_mfma_f32_16x16x32_bf16 v[82:85], v[146:149], v[190:193], v[82:85]
	v_mfma_f32_16x16x32_bf16 v[78:81], v[138:141], v[204:207], v[78:81]
	v_mfma_f32_16x16x32_bf16 v[74:77], v[146:149], v[204:207], v[74:77]
	v_mfma_f32_16x16x32_bf16 v[70:73], v[138:141], v[220:223], v[70:73]
	v_mfma_f32_16x16x32_bf16 v[66:69], v[146:149], v[220:223], v[66:69]
	v_mfma_f32_16x16x32_bf16 v[94:97], v[142:145], v[186:189], v[94:97]
	v_mfma_f32_16x16x32_bf16 v[90:93], v[150:153], v[186:189], v[90:93]
	v_mfma_f32_16x16x32_bf16 v[86:89], v[142:145], v[194:197], v[86:89]
	v_mfma_f32_16x16x32_bf16 v[82:85], v[150:153], v[194:197], v[82:85]
	v_mfma_f32_16x16x32_bf16 v[78:81], v[142:145], v[208:211], v[78:81]
	v_mfma_f32_16x16x32_bf16 v[74:77], v[150:153], v[208:211], v[74:77]
	v_mfma_f32_16x16x32_bf16 v[70:73], v[142:145], v[224:227], v[70:73]
	v_mfma_f32_16x16x32_bf16 v[66:69], v[150:153], v[224:227], v[66:69]
	s_setprio 0
	s_setprio 1
	v_mfma_f32_16x16x32_bf16 v[30:33], v[154:157], v[170:173], v[30:33]
	v_mfma_f32_16x16x32_bf16 v[26:29], v[162:165], v[170:173], v[26:29]
	v_mfma_f32_16x16x32_bf16 v[22:25], v[154:157], v[190:193], v[22:25]
	v_mfma_f32_16x16x32_bf16 v[18:21], v[162:165], v[190:193], v[18:21]
	v_mfma_f32_16x16x32_bf16 v[14:17], v[154:157], v[204:207], v[14:17]
	v_mfma_f32_16x16x32_bf16 v[10:13], v[162:165], v[204:207], v[10:13]
	v_mfma_f32_16x16x32_bf16 v[6:9], v[154:157], v[220:223], v[6:9]
	v_mfma_f32_16x16x32_bf16 v[2:5], v[162:165], v[220:223], v[2:5]
	v_mfma_f32_16x16x32_bf16 v[30:33], v[158:161], v[186:189], v[30:33]
	v_mfma_f32_16x16x32_bf16 v[26:29], v[166:169], v[186:189], v[26:29]
	v_mfma_f32_16x16x32_bf16 v[22:25], v[158:161], v[194:197], v[22:25]
	v_mfma_f32_16x16x32_bf16 v[18:21], v[166:169], v[194:197], v[18:21]
	v_mfma_f32_16x16x32_bf16 v[14:17], v[158:161], v[208:211], v[14:17]
	v_mfma_f32_16x16x32_bf16 v[10:13], v[166:169], v[208:211], v[10:13]
	v_mfma_f32_16x16x32_bf16 v[6:9], v[158:161], v[224:227], v[6:9]
	v_mfma_f32_16x16x32_bf16 v[2:5], v[166:169], v[224:227], v[2:5]
	s_setprio 0
	s_barrier
	s_add_i32 s71, 0, 0x18000
	v_add_u32_e32 v98, s71, v214
	s_add_i32 s72, 0, 0x1c000
	ds_read_b128 v[138:141], v98
	ds_read_b128 v[142:145], v98 offset:1024
	ds_read_b128 v[146:149], v98 offset:2048
	ds_read_b128 v[150:153], v98 offset:3072
	v_add_u32_e32 v98, s72, v214
	ds_read_b128 v[154:157], v98
	ds_read_b128 v[158:161], v98 offset:1024
	ds_read_b128 v[162:165], v98 offset:2048
	ds_read_b128 v[166:169], v98 offset:3072
	s_add_u32 s62, s62, 0x40000
	s_addc_u32 s63, s63, 0
	s_mov_b32 m0, s11
	v_lshl_add_u64 v[104:105], s[62:63], 0, v[174:175]
	ds_read_b128 v[170:173], v218 offset:32768
	ds_read_b128 v[186:189], v218 offset:33792
	ds_read_b128 v[190:193], v218 offset:34816
	ds_read_b128 v[194:197], v218 offset:35840
	ds_read_b128 v[204:207], v218 offset:36864
	ds_read_b128 v[208:211], v218 offset:37888
	ds_read_b128 v[220:223], v218 offset:38912
	ds_read_b128 v[224:227], v218 offset:39936
	s_setprio 1
	global_load_lds_dwordx4 v[104:105], off
	v_lshl_add_u64 v[104:105], s[62:63], 0, v[178:179]
	s_mov_b32 m0, s12
	s_nop 0
	global_load_lds_dwordx4 v[104:105], off
	s_waitcnt vmcnt(8) lgkmcnt(0)
	s_barrier
	v_mfma_f32_16x16x32_bf16 v[130:133], v[138:141], v[170:173], v[130:133]
	v_mfma_f32_16x16x32_bf16 v[126:129], v[146:149], v[170:173], v[126:129]
	v_mfma_f32_16x16x32_bf16 v[122:125], v[138:141], v[190:193], v[122:125]
	v_mfma_f32_16x16x32_bf16 v[118:121], v[146:149], v[190:193], v[118:121]
	v_mfma_f32_16x16x32_bf16 v[114:117], v[138:141], v[204:207], v[114:117]
	v_mfma_f32_16x16x32_bf16 v[110:113], v[146:149], v[204:207], v[110:113]
	v_mfma_f32_16x16x32_bf16 v[104:107], v[138:141], v[220:223], v[106:109]
	v_mfma_f32_16x16x32_bf16 v[100:103], v[146:149], v[220:223], v[100:103]
	v_mfma_f32_16x16x32_bf16 v[130:133], v[142:145], v[186:189], v[130:133]
	v_mfma_f32_16x16x32_bf16 v[126:129], v[150:153], v[186:189], v[126:129]
	v_mfma_f32_16x16x32_bf16 v[122:125], v[142:145], v[194:197], v[122:125]
	v_mfma_f32_16x16x32_bf16 v[118:121], v[150:153], v[194:197], v[118:121]
	v_mfma_f32_16x16x32_bf16 v[114:117], v[142:145], v[208:211], v[114:117]
	v_mfma_f32_16x16x32_bf16 v[110:113], v[150:153], v[208:211], v[110:113]
	v_mfma_f32_16x16x32_bf16 v[106:109], v[142:145], v[224:227], v[104:107]
	v_mfma_f32_16x16x32_bf16 v[102:105], v[150:153], v[224:227], v[100:103]
	s_setprio 0
	s_setprio 1
	v_mfma_f32_16x16x32_bf16 v[62:65], v[154:157], v[170:173], v[62:65]
	v_mfma_f32_16x16x32_bf16 v[58:61], v[162:165], v[170:173], v[58:61]
	v_mfma_f32_16x16x32_bf16 v[54:57], v[154:157], v[190:193], v[54:57]
	v_mfma_f32_16x16x32_bf16 v[50:53], v[162:165], v[190:193], v[50:53]
	v_mfma_f32_16x16x32_bf16 v[46:49], v[154:157], v[204:207], v[46:49]
	v_mfma_f32_16x16x32_bf16 v[42:45], v[162:165], v[204:207], v[42:45]
	v_mfma_f32_16x16x32_bf16 v[38:41], v[154:157], v[220:223], v[38:41]
	v_mfma_f32_16x16x32_bf16 v[34:37], v[162:165], v[220:223], v[34:37]
	v_mfma_f32_16x16x32_bf16 v[62:65], v[158:161], v[186:189], v[62:65]
	v_mfma_f32_16x16x32_bf16 v[58:61], v[166:169], v[186:189], v[58:61]
	v_mfma_f32_16x16x32_bf16 v[54:57], v[158:161], v[194:197], v[54:57]
	v_mfma_f32_16x16x32_bf16 v[50:53], v[166:169], v[194:197], v[50:53]
	v_mfma_f32_16x16x32_bf16 v[46:49], v[158:161], v[208:211], v[46:49]
	v_mfma_f32_16x16x32_bf16 v[42:45], v[166:169], v[208:211], v[42:45]
	v_mfma_f32_16x16x32_bf16 v[38:41], v[158:161], v[224:227], v[38:41]
	v_mfma_f32_16x16x32_bf16 v[34:37], v[166:169], v[224:227], v[34:37]
	s_barrier
	s_add_i32 s62, s71, s4
	v_lshl_add_u64 v[100:101], v[198:199], 0, s[28:29]
	s_mov_b32 m0, s62
	ds_read_b128 v[170:173], v218 offset:49152
	ds_read_b128 v[186:189], v218 offset:50176
	ds_read_b128 v[190:193], v218 offset:51200
	ds_read_b128 v[194:197], v218 offset:52224
	ds_read_b128 v[204:207], v218 offset:53248
	ds_read_b128 v[208:211], v218 offset:54272
	ds_read_b128 v[220:223], v218 offset:55296
	ds_read_b128 v[224:227], v218 offset:56320
	global_load_lds_dwordx4 v[100:101], off
	s_add_i32 m0, s62, 0x2000
	s_add_u32 s60, s60, 0x40080
	v_lshl_add_u64 v[100:101], v[228:229], 0, s[28:29]
	s_addc_u32 s61, s61, 0
	s_add_i32 s62, s72, s4
	global_load_lds_dwordx4 v[100:101], off
	v_lshl_add_u64 v[100:101], s[60:61], 0, v[176:177]
	s_mov_b32 m0, s62
	s_nop 0
	global_load_lds_dwordx4 v[100:101], off
	v_lshl_add_u64 v[100:101], s[60:61], 0, v[180:181]
	s_add_i32 m0, s62, 0x2000
	s_nop 0
	global_load_lds_dwordx4 v[100:101], off
	v_lshl_add_u64 v[100:101], v[230:231], 0, s[28:29]
	s_mov_b32 m0, s15
	s_nop 0
	global_load_lds_dwordx4 v[100:101], off
	v_lshl_add_u64 v[100:101], v[232:233], 0, s[28:29]
	s_mov_b32 m0, s16
	s_nop 0
	global_load_lds_dwordx4 v[100:101], off
	s_waitcnt vmcnt(8) lgkmcnt(0)
	s_barrier
	v_mfma_f32_16x16x32_bf16 v[94:97], v[138:141], v[170:173], v[94:97]
	v_mfma_f32_16x16x32_bf16 v[90:93], v[146:149], v[170:173], v[90:93]
	v_mfma_f32_16x16x32_bf16 v[86:89], v[138:141], v[190:193], v[86:89]
	v_mfma_f32_16x16x32_bf16 v[82:85], v[146:149], v[190:193], v[82:85]
	v_mfma_f32_16x16x32_bf16 v[78:81], v[138:141], v[204:207], v[78:81]
	v_mfma_f32_16x16x32_bf16 v[74:77], v[146:149], v[204:207], v[74:77]
	v_mfma_f32_16x16x32_bf16 v[70:73], v[138:141], v[220:223], v[70:73]
	v_mfma_f32_16x16x32_bf16 v[66:69], v[146:149], v[220:223], v[66:69]
	v_mfma_f32_16x16x32_bf16 v[94:97], v[142:145], v[186:189], v[94:97]
	v_mfma_f32_16x16x32_bf16 v[90:93], v[150:153], v[186:189], v[90:93]
	v_mfma_f32_16x16x32_bf16 v[86:89], v[142:145], v[194:197], v[86:89]
	v_mfma_f32_16x16x32_bf16 v[82:85], v[150:153], v[194:197], v[82:85]
	v_mfma_f32_16x16x32_bf16 v[78:81], v[142:145], v[208:211], v[78:81]
	v_mfma_f32_16x16x32_bf16 v[74:77], v[150:153], v[208:211], v[74:77]
	v_mfma_f32_16x16x32_bf16 v[70:73], v[142:145], v[224:227], v[70:73]
	v_mfma_f32_16x16x32_bf16 v[66:69], v[150:153], v[224:227], v[66:69]
	s_setprio 0
	s_setprio 1
	v_mfma_f32_16x16x32_bf16 v[30:33], v[154:157], v[170:173], v[30:33]
	v_mfma_f32_16x16x32_bf16 v[26:29], v[162:165], v[170:173], v[26:29]
	v_mfma_f32_16x16x32_bf16 v[22:25], v[154:157], v[190:193], v[22:25]
	v_mfma_f32_16x16x32_bf16 v[18:21], v[162:165], v[190:193], v[18:21]
	v_mfma_f32_16x16x32_bf16 v[14:17], v[154:157], v[204:207], v[14:17]
	v_mfma_f32_16x16x32_bf16 v[10:13], v[162:165], v[204:207], v[10:13]
	v_mfma_f32_16x16x32_bf16 v[6:9], v[154:157], v[220:223], v[6:9]
	v_mfma_f32_16x16x32_bf16 v[2:5], v[162:165], v[220:223], v[2:5]
	v_mfma_f32_16x16x32_bf16 v[30:33], v[158:161], v[186:189], v[30:33]
	v_mfma_f32_16x16x32_bf16 v[26:29], v[166:169], v[186:189], v[26:29]
	v_mfma_f32_16x16x32_bf16 v[22:25], v[158:161], v[194:197], v[22:25]
	v_mfma_f32_16x16x32_bf16 v[18:21], v[166:169], v[194:197], v[18:21]
	v_mfma_f32_16x16x32_bf16 v[14:17], v[158:161], v[208:211], v[14:17]
	v_mfma_f32_16x16x32_bf16 v[10:13], v[166:169], v[208:211], v[10:13]
	v_mfma_f32_16x16x32_bf16 v[6:9], v[158:161], v[224:227], v[6:9]
	v_mfma_f32_16x16x32_bf16 v[2:5], v[166:169], v[224:227], v[2:5]
	s_setprio 0
	s_barrier
	s_add_u32 s58, s58, 0x100
	s_addc_u32 s59, s59, 0
	s_cmp_gt_u32 s70, 13
	s_cbranch_scc1 .LBB0_1075

.LBB0_1110:
	s_add_i32 s75, s75, 2
	s_add_u32 s60, s38, s58
	s_addc_u32 s61, s39, s59
	s_add_u32 s60, s60, 0x100
	s_addc_u32 s61, s61, 0
	s_add_u32 s76, s72, s58
	s_addc_u32 s77, s73, s59
	s_add_i32 s78, 0, 0x10000
	s_cmp_eq_u32 s74, s58
	s_cselect_b32 s63, s49, s61
	s_cselect_b32 s62, s70, s60
	v_add_u32_e32 v98, s78, v177
	s_cselect_b32 s61, s45, s77
	s_cselect_b32 s60, s71, s76
	s_add_i32 s79, 0, 0x14000
	ds_read_b128 v[138:141], v98
	ds_read_b128 v[142:145], v98 offset:1024
	ds_read_b128 v[146:149], v98 offset:2048
	ds_read_b128 v[150:153], v98 offset:3072
	v_add_u32_e32 v98, s79, v177
	ds_read_b128 v[154:157], v98
	ds_read_b128 v[170:173], v98 offset:1024
	ds_read_b128 v[182:185], v98 offset:2048
	ds_read_b128 v[186:189], v98 offset:3072
	v_lshl_add_u64 v[100:101], v[134:135], 0, s[58:59]
	s_add_i32 m0, s10, 0xc000
	ds_read_b128 v[190:193], v181
	ds_read_b128 v[194:197], v181 offset:1024
	ds_read_b128 v[204:207], v181 offset:2048
	ds_read_b128 v[208:211], v181 offset:3072
	ds_read_b128 v[214:217], v181 offset:4096
	ds_read_b128 v[218:221], v181 offset:5120
	ds_read_b128 v[222:225], v181 offset:6144
	ds_read_b128 v[226:229], v181 offset:7168
	s_setprio 1
	global_load_lds_dwordx4 v[100:101], off
	v_lshl_add_u64 v[100:101], v[136:137], 0, s[58:59]
	s_add_i32 m0, s10, 0xe000
	s_nop 0
	global_load_lds_dwordx4 v[100:101], off
	s_waitcnt vmcnt(8) lgkmcnt(0)
	s_barrier
	v_mfma_f32_16x16x32_bf16 v[130:133], v[138:141], v[190:193], v[130:133]
	v_mfma_f32_16x16x32_bf16 v[126:129], v[146:149], v[190:193], v[126:129]
	v_mfma_f32_16x16x32_bf16 v[114:117], v[138:141], v[204:207], v[114:117]
	v_mfma_f32_16x16x32_bf16 v[110:113], v[146:149], v[204:207], v[110:113]
	v_mfma_f32_16x16x32_bf16 v[94:97], v[138:141], v[214:217], v[94:97]
	v_mfma_f32_16x16x32_bf16 v[90:93], v[146:149], v[214:217], v[90:93]
	v_mfma_f32_16x16x32_bf16 v[78:81], v[138:141], v[222:225], v[78:81]
	v_mfma_f32_16x16x32_bf16 v[74:77], v[146:149], v[222:225], v[74:77]
	v_mfma_f32_16x16x32_bf16 v[130:133], v[142:145], v[194:197], v[130:133]
	v_mfma_f32_16x16x32_bf16 v[126:129], v[150:153], v[194:197], v[126:129]
	v_mfma_f32_16x16x32_bf16 v[114:117], v[142:145], v[208:211], v[114:117]
	v_mfma_f32_16x16x32_bf16 v[110:113], v[150:153], v[208:211], v[110:113]
	v_mfma_f32_16x16x32_bf16 v[94:97], v[142:145], v[218:221], v[94:97]
	v_mfma_f32_16x16x32_bf16 v[90:93], v[150:153], v[218:221], v[90:93]
	v_mfma_f32_16x16x32_bf16 v[78:81], v[142:145], v[226:229], v[78:81]
	v_mfma_f32_16x16x32_bf16 v[74:77], v[150:153], v[226:229], v[74:77]
	s_setprio 0
	s_setprio 1
	v_mfma_f32_16x16x32_bf16 v[122:125], v[154:157], v[190:193], v[122:125]
	v_mfma_f32_16x16x32_bf16 v[118:121], v[182:185], v[190:193], v[118:121]
	v_mfma_f32_16x16x32_bf16 v[106:109], v[154:157], v[204:207], v[106:109]
	v_mfma_f32_16x16x32_bf16 v[100:103], v[182:185], v[204:207], v[102:105]
	v_mfma_f32_16x16x32_bf16 v[86:89], v[154:157], v[214:217], v[86:89]
	v_mfma_f32_16x16x32_bf16 v[82:85], v[182:185], v[214:217], v[82:85]
	v_mfma_f32_16x16x32_bf16 v[70:73], v[154:157], v[222:225], v[70:73]
	v_mfma_f32_16x16x32_bf16 v[66:69], v[182:185], v[222:225], v[66:69]
	v_mfma_f32_16x16x32_bf16 v[122:125], v[170:173], v[194:197], v[122:125]
	v_mfma_f32_16x16x32_bf16 v[118:121], v[186:189], v[194:197], v[118:121]
	v_mfma_f32_16x16x32_bf16 v[106:109], v[170:173], v[208:211], v[106:109]
	v_mfma_f32_16x16x32_bf16 v[100:103], v[186:189], v[208:211], v[100:103]
	v_mfma_f32_16x16x32_bf16 v[86:89], v[170:173], v[218:221], v[86:89]
	v_mfma_f32_16x16x32_bf16 v[82:85], v[186:189], v[218:221], v[82:85]
	v_mfma_f32_16x16x32_bf16 v[70:73], v[170:173], v[226:229], v[70:73]
	v_mfma_f32_16x16x32_bf16 v[66:69], v[186:189], v[226:229], v[66:69]
	s_barrier
	s_add_i32 s76, s78, s9
	v_lshl_add_u64 v[174:175], s[60:61], 0, v[162:163]
	s_mov_b32 m0, s76
	ds_read_b128 v[190:193], v181 offset:16384
	ds_read_b128 v[194:197], v181 offset:17408
	ds_read_b128 v[204:207], v181 offset:18432
	ds_read_b128 v[208:211], v181 offset:19456
	ds_read_b128 v[214:217], v181 offset:20480
	ds_read_b128 v[218:221], v181 offset:21504
	ds_read_b128 v[222:225], v181 offset:22528
	ds_read_b128 v[226:229], v181 offset:23552
	global_load_lds_dwordx4 v[174:175], off
	s_add_i32 m0, s76, 0x2000
	s_add_u32 s76, s60, 0x40000
	v_lshl_add_u64 v[198:199], s[60:61], 0, v[158:159]
	s_addc_u32 s77, s61, 0
	s_add_i32 s78, s79, s9
	global_load_lds_dwordx4 v[198:199], off
	v_lshl_add_u64 v[104:105], s[76:77], 0, v[162:163]
	s_mov_b32 m0, s78
	v_lshl_add_u64 v[230:231], s[62:63], 0, v[164:165]
	global_load_lds_dwordx4 v[104:105], off
	v_lshl_add_u64 v[104:105], s[76:77], 0, v[158:159]
	s_add_i32 m0, s78, 0x2000
	v_lshl_add_u64 v[232:233], s[62:63], 0, v[160:161]
	global_load_lds_dwordx4 v[104:105], off
	s_mov_b32 m0, s10
	s_nop 0
	global_load_lds_dwordx4 v[230:231], off
	s_mov_b32 m0, s11
	s_nop 0
	global_load_lds_dwordx4 v[232:233], off
	s_waitcnt vmcnt(8) lgkmcnt(0)
	s_barrier
	v_mfma_f32_16x16x32_bf16 v[62:65], v[138:141], v[190:193], v[62:65]
	v_mfma_f32_16x16x32_bf16 v[58:61], v[146:149], v[190:193], v[58:61]
	v_mfma_f32_16x16x32_bf16 v[46:49], v[138:141], v[204:207], v[46:49]
	v_mfma_f32_16x16x32_bf16 v[42:45], v[146:149], v[204:207], v[42:45]
	v_mfma_f32_16x16x32_bf16 v[30:33], v[138:141], v[214:217], v[30:33]
	v_mfma_f32_16x16x32_bf16 v[26:29], v[146:149], v[214:217], v[26:29]
	v_mfma_f32_16x16x32_bf16 v[14:17], v[138:141], v[222:225], v[14:17]
	v_mfma_f32_16x16x32_bf16 v[10:13], v[146:149], v[222:225], v[10:13]
	v_mfma_f32_16x16x32_bf16 v[62:65], v[142:145], v[194:197], v[62:65]
	v_mfma_f32_16x16x32_bf16 v[58:61], v[150:153], v[194:197], v[58:61]
	v_mfma_f32_16x16x32_bf16 v[46:49], v[142:145], v[208:211], v[46:49]
	v_mfma_f32_16x16x32_bf16 v[42:45], v[150:153], v[208:211], v[42:45]
	v_mfma_f32_16x16x32_bf16 v[30:33], v[142:145], v[218:221], v[30:33]
	v_mfma_f32_16x16x32_bf16 v[26:29], v[150:153], v[218:221], v[26:29]
	v_mfma_f32_16x16x32_bf16 v[14:17], v[142:145], v[226:229], v[14:17]
	v_mfma_f32_16x16x32_bf16 v[10:13], v[150:153], v[226:229], v[10:13]
	s_setprio 0
	s_setprio 1
	v_mfma_f32_16x16x32_bf16 v[54:57], v[154:157], v[190:193], v[54:57]
	v_mfma_f32_16x16x32_bf16 v[50:53], v[182:185], v[190:193], v[50:53]
	v_mfma_f32_16x16x32_bf16 v[38:41], v[154:157], v[204:207], v[38:41]
	v_mfma_f32_16x16x32_bf16 v[34:37], v[182:185], v[204:207], v[34:37]
	v_mfma_f32_16x16x32_bf16 v[22:25], v[154:157], v[214:217], v[22:25]
	v_mfma_f32_16x16x32_bf16 v[18:21], v[182:185], v[214:217], v[18:21]
	v_mfma_f32_16x16x32_bf16 v[6:9], v[154:157], v[222:225], v[6:9]
	v_mfma_f32_16x16x32_bf16 v[2:5], v[182:185], v[222:225], v[2:5]
	v_mfma_f32_16x16x32_bf16 v[54:57], v[170:173], v[194:197], v[54:57]
	v_mfma_f32_16x16x32_bf16 v[50:53], v[186:189], v[194:197], v[50:53]
	v_mfma_f32_16x16x32_bf16 v[38:41], v[170:173], v[208:211], v[38:41]
	v_mfma_f32_16x16x32_bf16 v[34:37], v[186:189], v[208:211], v[34:37]
	v_mfma_f32_16x16x32_bf16 v[22:25], v[170:173], v[218:221], v[22:25]
	v_mfma_f32_16x16x32_bf16 v[18:21], v[186:189], v[218:221], v[18:21]
	v_mfma_f32_16x16x32_bf16 v[6:9], v[170:173], v[226:229], v[6:9]
	v_mfma_f32_16x16x32_bf16 v[2:5], v[186:189], v[226:229], v[2:5]
	s_setprio 0
	s_barrier
	s_add_i32 s76, 0, 0x18000
	v_add_u32_e32 v98, s76, v177
	s_add_i32 s77, 0, 0x1c000
	ds_read_b128 v[138:141], v98
	ds_read_b128 v[142:145], v98 offset:1024
	ds_read_b128 v[146:149], v98 offset:2048
	ds_read_b128 v[150:153], v98 offset:3072
	v_add_u32_e32 v98, s77, v177
	ds_read_b128 v[154:157], v98
	ds_read_b128 v[170:173], v98 offset:1024
	ds_read_b128 v[182:185], v98 offset:2048
	ds_read_b128 v[186:189], v98 offset:3072
	s_add_u32 s62, s62, 0x40000
	s_addc_u32 s63, s63, 0
	s_mov_b32 m0, s12
	v_lshl_add_u64 v[104:105], s[62:63], 0, v[164:165]
	ds_read_b128 v[190:193], v181 offset:32768
	ds_read_b128 v[194:197], v181 offset:33792
	ds_read_b128 v[204:207], v181 offset:34816
	ds_read_b128 v[208:211], v181 offset:35840
	ds_read_b128 v[214:217], v181 offset:36864
	ds_read_b128 v[218:221], v181 offset:37888
	ds_read_b128 v[222:225], v181 offset:38912
	ds_read_b128 v[226:229], v181 offset:39936
	s_setprio 1
	global_load_lds_dwordx4 v[104:105], off
	v_lshl_add_u64 v[104:105], s[62:63], 0, v[160:161]
	s_mov_b32 m0, s13
	s_nop 0
	global_load_lds_dwordx4 v[104:105], off
	s_waitcnt vmcnt(8) lgkmcnt(0)
	s_barrier
	v_mfma_f32_16x16x32_bf16 v[130:133], v[138:141], v[190:193], v[130:133]
	v_mfma_f32_16x16x32_bf16 v[126:129], v[146:149], v[190:193], v[126:129]
	v_mfma_f32_16x16x32_bf16 v[114:117], v[138:141], v[204:207], v[114:117]
	v_mfma_f32_16x16x32_bf16 v[110:113], v[146:149], v[204:207], v[110:113]
	v_mfma_f32_16x16x32_bf16 v[94:97], v[138:141], v[214:217], v[94:97]
	v_mfma_f32_16x16x32_bf16 v[90:93], v[146:149], v[214:217], v[90:93]
	v_mfma_f32_16x16x32_bf16 v[78:81], v[138:141], v[222:225], v[78:81]
	v_mfma_f32_16x16x32_bf16 v[74:77], v[146:149], v[222:225], v[74:77]
	v_mfma_f32_16x16x32_bf16 v[130:133], v[142:145], v[194:197], v[130:133]
	v_mfma_f32_16x16x32_bf16 v[126:129], v[150:153], v[194:197], v[126:129]
	v_mfma_f32_16x16x32_bf16 v[114:117], v[142:145], v[208:211], v[114:117]
	v_mfma_f32_16x16x32_bf16 v[110:113], v[150:153], v[208:211], v[110:113]
	v_mfma_f32_16x16x32_bf16 v[94:97], v[142:145], v[218:221], v[94:97]
	v_mfma_f32_16x16x32_bf16 v[90:93], v[150:153], v[218:221], v[90:93]
	v_mfma_f32_16x16x32_bf16 v[78:81], v[142:145], v[226:229], v[78:81]
	v_mfma_f32_16x16x32_bf16 v[74:77], v[150:153], v[226:229], v[74:77]
	s_setprio 0
	s_setprio 1
	v_mfma_f32_16x16x32_bf16 v[122:125], v[154:157], v[190:193], v[122:125]
	v_mfma_f32_16x16x32_bf16 v[118:121], v[182:185], v[190:193], v[118:121]
	v_mfma_f32_16x16x32_bf16 v[104:107], v[154:157], v[204:207], v[106:109]
	v_mfma_f32_16x16x32_bf16 v[100:103], v[182:185], v[204:207], v[100:103]
	v_mfma_f32_16x16x32_bf16 v[86:89], v[154:157], v[214:217], v[86:89]
	v_mfma_f32_16x16x32_bf16 v[82:85], v[182:185], v[214:217], v[82:85]
	v_mfma_f32_16x16x32_bf16 v[70:73], v[154:157], v[222:225], v[70:73]
	v_mfma_f32_16x16x32_bf16 v[66:69], v[182:185], v[222:225], v[66:69]
	v_mfma_f32_16x16x32_bf16 v[122:125], v[170:173], v[194:197], v[122:125]
	v_mfma_f32_16x16x32_bf16 v[118:121], v[186:189], v[194:197], v[118:121]
	v_mfma_f32_16x16x32_bf16 v[106:109], v[170:173], v[208:211], v[104:107]
	v_mfma_f32_16x16x32_bf16 v[102:105], v[186:189], v[208:211], v[100:103]
	v_mfma_f32_16x16x32_bf16 v[86:89], v[170:173], v[218:221], v[86:89]
	v_mfma_f32_16x16x32_bf16 v[82:85], v[186:189], v[218:221], v[82:85]
	v_mfma_f32_16x16x32_bf16 v[70:73], v[170:173], v[226:229], v[70:73]
	v_mfma_f32_16x16x32_bf16 v[66:69], v[186:189], v[226:229], v[66:69]
	s_barrier
	s_add_i32 s62, s76, s9
	v_lshl_add_u64 v[100:101], v[174:175], 0, s[28:29]
	s_mov_b32 m0, s62
	ds_read_b128 v[190:193], v181 offset:49152
	ds_read_b128 v[194:197], v181 offset:50176
	ds_read_b128 v[204:207], v181 offset:51200
	ds_read_b128 v[208:211], v181 offset:52224
	ds_read_b128 v[214:217], v181 offset:53248
	ds_read_b128 v[218:221], v181 offset:54272
	ds_read_b128 v[222:225], v181 offset:55296
	ds_read_b128 v[226:229], v181 offset:56320
	global_load_lds_dwordx4 v[100:101], off
	s_add_i32 m0, s62, 0x2000
	s_add_u32 s60, s60, 0x40080
	v_lshl_add_u64 v[100:101], v[198:199], 0, s[28:29]
	s_addc_u32 s61, s61, 0
	s_add_i32 s62, s77, s9
	global_load_lds_dwordx4 v[100:101], off
	v_lshl_add_u64 v[100:101], s[60:61], 0, v[162:163]
	s_mov_b32 m0, s62
	s_nop 0
	global_load_lds_dwordx4 v[100:101], off
	v_lshl_add_u64 v[100:101], s[60:61], 0, v[158:159]
	s_add_i32 m0, s62, 0x2000
	s_nop 0
	global_load_lds_dwordx4 v[100:101], off
	v_lshl_add_u64 v[100:101], v[230:231], 0, s[28:29]
	s_mov_b32 m0, s16
	s_nop 0
	global_load_lds_dwordx4 v[100:101], off
	v_lshl_add_u64 v[100:101], v[232:233], 0, s[28:29]
	s_mov_b32 m0, s17
	s_nop 0
	global_load_lds_dwordx4 v[100:101], off
	s_waitcnt vmcnt(8) lgkmcnt(0)
	s_barrier
	v_mfma_f32_16x16x32_bf16 v[62:65], v[138:141], v[190:193], v[62:65]
	v_mfma_f32_16x16x32_bf16 v[58:61], v[146:149], v[190:193], v[58:61]
	v_mfma_f32_16x16x32_bf16 v[46:49], v[138:141], v[204:207], v[46:49]
	v_mfma_f32_16x16x32_bf16 v[42:45], v[146:149], v[204:207], v[42:45]
	v_mfma_f32_16x16x32_bf16 v[30:33], v[138:141], v[214:217], v[30:33]
	v_mfma_f32_16x16x32_bf16 v[26:29], v[146:149], v[214:217], v[26:29]
	v_mfma_f32_16x16x32_bf16 v[14:17], v[138:141], v[222:225], v[14:17]
	v_mfma_f32_16x16x32_bf16 v[10:13], v[146:149], v[222:225], v[10:13]
	v_mfma_f32_16x16x32_bf16 v[62:65], v[142:145], v[194:197], v[62:65]
	v_mfma_f32_16x16x32_bf16 v[58:61], v[150:153], v[194:197], v[58:61]
	v_mfma_f32_16x16x32_bf16 v[46:49], v[142:145], v[208:211], v[46:49]
	v_mfma_f32_16x16x32_bf16 v[42:45], v[150:153], v[208:211], v[42:45]
	v_mfma_f32_16x16x32_bf16 v[30:33], v[142:145], v[218:221], v[30:33]
	v_mfma_f32_16x16x32_bf16 v[26:29], v[150:153], v[218:221], v[26:29]
	v_mfma_f32_16x16x32_bf16 v[14:17], v[142:145], v[226:229], v[14:17]
	v_mfma_f32_16x16x32_bf16 v[10:13], v[150:153], v[226:229], v[10:13]
	s_setprio 0
	s_setprio 1
	v_mfma_f32_16x16x32_bf16 v[54:57], v[154:157], v[190:193], v[54:57]
	v_mfma_f32_16x16x32_bf16 v[50:53], v[182:185], v[190:193], v[50:53]
	v_mfma_f32_16x16x32_bf16 v[38:41], v[154:157], v[204:207], v[38:41]
	v_mfma_f32_16x16x32_bf16 v[34:37], v[182:185], v[204:207], v[34:37]
	v_mfma_f32_16x16x32_bf16 v[22:25], v[154:157], v[214:217], v[22:25]
	v_mfma_f32_16x16x32_bf16 v[18:21], v[182:185], v[214:217], v[18:21]
	v_mfma_f32_16x16x32_bf16 v[6:9], v[154:157], v[222:225], v[6:9]
	v_mfma_f32_16x16x32_bf16 v[2:5], v[182:185], v[222:225], v[2:5]
	v_mfma_f32_16x16x32_bf16 v[54:57], v[170:173], v[194:197], v[54:57]
	v_mfma_f32_16x16x32_bf16 v[50:53], v[186:189], v[194:197], v[50:53]
	v_mfma_f32_16x16x32_bf16 v[38:41], v[170:173], v[208:211], v[38:41]
	v_mfma_f32_16x16x32_bf16 v[34:37], v[186:189], v[208:211], v[34:37]
	v_mfma_f32_16x16x32_bf16 v[22:25], v[170:173], v[218:221], v[22:25]
	v_mfma_f32_16x16x32_bf16 v[18:21], v[186:189], v[218:221], v[18:21]
	v_mfma_f32_16x16x32_bf16 v[6:9], v[170:173], v[226:229], v[6:9]
	v_mfma_f32_16x16x32_bf16 v[2:5], v[186:189], v[226:229], v[2:5]
	s_setprio 0
	s_barrier
	s_add_u32 s58, s58, 0x100
	s_addc_u32 s59, s59, 0
	s_cmp_ge_u32 s75, s57
	s_cbranch_scc1 .LBB0_1113

.LBB0_1529:
	s_add_u32 s50, s48, 0x100
	s_addc_u32 s51, s49, 0
	s_add_i32 s58, 0, 0x10000
	s_cmp_eq_u32 s57, 40
	s_cselect_b32 s55, s1, s51
	s_cselect_b32 s54, s0, s50
	s_cselect_b32 s53, s47, s56
	s_cselect_b32 s52, s46, s33
	s_add_i32 s59, 0, 0x14000
	v_add_u32_e32 v144, s58, v186
	v_add_u32_e32 v160, s59, v186
	ds_read_b128 v[132:135], v144
	ds_read_b128 v[136:139], v144 offset:1024
	ds_read_b128 v[140:143], v144 offset:2048
	ds_read_b128 v[144:147], v144 offset:3072
	ds_read_b128 v[148:151], v160
	ds_read_b128 v[152:155], v160 offset:1024
	ds_read_b128 v[156:159], v160 offset:2048
	ds_read_b128 v[160:163], v160 offset:3072
	v_lshl_add_u64 v[214:215], s[48:49], 0, v[174:175]
	s_add_i32 m0, s4, 0xc000
	ds_read_b128 v[164:167], v187
	ds_read_b128 v[178:181], v187 offset:1024
	ds_read_b128 v[182:185], v187 offset:2048
	ds_read_b128 v[188:191], v187 offset:3072
	ds_read_b128 v[192:195], v187 offset:4096
	ds_read_b128 v[196:199], v187 offset:5120
	ds_read_b128 v[204:207], v187 offset:6144
	ds_read_b128 v[208:211], v187 offset:7168
	s_setprio 1
	global_load_lds_dwordx4 v[214:215], off
	v_lshl_add_u64 v[214:215], s[48:49], 0, v[176:177]
	s_add_i32 m0, s4, 0xe000
	s_nop 0
	global_load_lds_dwordx4 v[214:215], off
	s_waitcnt vmcnt(8) lgkmcnt(0)
	s_barrier
	v_mfma_f32_16x16x32_bf16 v[128:131], v[132:135], v[164:167], v[128:131]
	v_mfma_f32_16x16x32_bf16 v[124:127], v[140:143], v[164:167], v[124:127]
	v_mfma_f32_16x16x32_bf16 v[120:123], v[132:135], v[182:185], v[120:123]
	v_mfma_f32_16x16x32_bf16 v[116:119], v[140:143], v[182:185], v[116:119]
	v_mfma_f32_16x16x32_bf16 v[112:115], v[132:135], v[192:195], v[112:115]
	v_mfma_f32_16x16x32_bf16 v[108:111], v[140:143], v[192:195], v[108:111]
	v_mfma_f32_16x16x32_bf16 v[104:107], v[132:135], v[204:207], v[104:107]
	v_mfma_f32_16x16x32_bf16 v[100:103], v[140:143], v[204:207], v[100:103]
	v_mfma_f32_16x16x32_bf16 v[128:131], v[136:139], v[178:181], v[128:131]
	v_mfma_f32_16x16x32_bf16 v[124:127], v[144:147], v[178:181], v[124:127]
	v_mfma_f32_16x16x32_bf16 v[120:123], v[136:139], v[188:191], v[120:123]
	v_mfma_f32_16x16x32_bf16 v[116:119], v[144:147], v[188:191], v[116:119]
	v_mfma_f32_16x16x32_bf16 v[112:115], v[136:139], v[196:199], v[112:115]
	v_mfma_f32_16x16x32_bf16 v[108:111], v[144:147], v[196:199], v[108:111]
	v_mfma_f32_16x16x32_bf16 v[104:107], v[136:139], v[208:211], v[104:107]
	v_mfma_f32_16x16x32_bf16 v[100:103], v[144:147], v[208:211], v[100:103]
	s_setprio 0
	s_setprio 1
	v_mfma_f32_16x16x32_bf16 v[62:65], v[148:151], v[164:167], v[62:65]
	v_mfma_f32_16x16x32_bf16 v[58:61], v[156:159], v[164:167], v[58:61]
	v_mfma_f32_16x16x32_bf16 v[54:57], v[148:151], v[182:185], v[54:57]
	v_mfma_f32_16x16x32_bf16 v[50:53], v[156:159], v[182:185], v[50:53]
	v_mfma_f32_16x16x32_bf16 v[46:49], v[148:151], v[192:195], v[46:49]
	v_mfma_f32_16x16x32_bf16 v[42:45], v[156:159], v[192:195], v[42:45]
	v_mfma_f32_16x16x32_bf16 v[38:41], v[148:151], v[204:207], v[38:41]
	v_mfma_f32_16x16x32_bf16 v[34:37], v[156:159], v[204:207], v[34:37]
	v_mfma_f32_16x16x32_bf16 v[62:65], v[152:155], v[178:181], v[62:65]
	v_mfma_f32_16x16x32_bf16 v[58:61], v[160:163], v[178:181], v[58:61]
	v_mfma_f32_16x16x32_bf16 v[54:57], v[152:155], v[188:191], v[54:57]
	v_mfma_f32_16x16x32_bf16 v[50:53], v[160:163], v[188:191], v[50:53]
	v_mfma_f32_16x16x32_bf16 v[46:49], v[152:155], v[196:199], v[46:49]
	v_mfma_f32_16x16x32_bf16 v[42:45], v[160:163], v[196:199], v[42:45]
	v_mfma_f32_16x16x32_bf16 v[38:41], v[152:155], v[208:211], v[38:41]
	v_mfma_f32_16x16x32_bf16 v[34:37], v[160:163], v[208:211], v[34:37]
	s_barrier
	s_add_i32 s48, s58, s2
	v_lshl_add_u64 v[214:215], s[52:53], 0, v[98:99]
	s_mov_b32 m0, s48
	ds_read_b128 v[164:167], v187 offset:16384
	ds_read_b128 v[178:181], v187 offset:17408
	ds_read_b128 v[182:185], v187 offset:18432
	ds_read_b128 v[188:191], v187 offset:19456
	ds_read_b128 v[192:195], v187 offset:20480
	ds_read_b128 v[196:199], v187 offset:21504
	ds_read_b128 v[204:207], v187 offset:22528
	ds_read_b128 v[208:211], v187 offset:23552
	global_load_lds_dwordx4 v[214:215], off
	s_add_i32 m0, s48, 0x2000
	s_add_u32 s48, s52, 0xb0000
	v_lshl_add_u64 v[216:217], s[52:53], 0, v[168:169]
	s_addc_u32 s49, s53, 0
	s_add_i32 s58, s59, s2
	global_load_lds_dwordx4 v[216:217], off
	v_lshl_add_u64 v[218:219], s[48:49], 0, v[98:99]
	s_mov_b32 m0, s58
	v_lshl_add_u64 v[220:221], s[54:55], 0, v[170:171]
	global_load_lds_dwordx4 v[218:219], off
	v_lshl_add_u64 v[218:219], s[48:49], 0, v[168:169]
	s_add_i32 m0, s58, 0x2000
	s_nop 0
	global_load_lds_dwordx4 v[218:219], off
	v_lshl_add_u64 v[218:219], s[54:55], 0, v[172:173]
	s_mov_b32 m0, s4
	s_nop 0
	global_load_lds_dwordx4 v[218:219], off
	s_mov_b32 m0, s7
	s_nop 0
	global_load_lds_dwordx4 v[220:221], off
	s_waitcnt vmcnt(8) lgkmcnt(0)
	s_barrier
	v_mfma_f32_16x16x32_bf16 v[94:97], v[132:135], v[164:167], v[94:97]
	v_mfma_f32_16x16x32_bf16 v[90:93], v[140:143], v[164:167], v[90:93]
	v_mfma_f32_16x16x32_bf16 v[86:89], v[132:135], v[182:185], v[86:89]
	v_mfma_f32_16x16x32_bf16 v[82:85], v[140:143], v[182:185], v[82:85]
	v_mfma_f32_16x16x32_bf16 v[78:81], v[132:135], v[192:195], v[78:81]
	v_mfma_f32_16x16x32_bf16 v[74:77], v[140:143], v[192:195], v[74:77]
	v_mfma_f32_16x16x32_bf16 v[70:73], v[132:135], v[204:207], v[70:73]
	v_mfma_f32_16x16x32_bf16 v[66:69], v[140:143], v[204:207], v[66:69]
	v_mfma_f32_16x16x32_bf16 v[94:97], v[136:139], v[178:181], v[94:97]
	v_mfma_f32_16x16x32_bf16 v[90:93], v[144:147], v[178:181], v[90:93]
	v_mfma_f32_16x16x32_bf16 v[86:89], v[136:139], v[188:191], v[86:89]
	v_mfma_f32_16x16x32_bf16 v[82:85], v[144:147], v[188:191], v[82:85]
	v_mfma_f32_16x16x32_bf16 v[78:81], v[136:139], v[196:199], v[78:81]
	v_mfma_f32_16x16x32_bf16 v[74:77], v[144:147], v[196:199], v[74:77]
	v_mfma_f32_16x16x32_bf16 v[70:73], v[136:139], v[208:211], v[70:73]
	v_mfma_f32_16x16x32_bf16 v[66:69], v[144:147], v[208:211], v[66:69]
	s_setprio 0
	s_setprio 1
	v_mfma_f32_16x16x32_bf16 v[30:33], v[148:151], v[164:167], v[30:33]
	v_mfma_f32_16x16x32_bf16 v[26:29], v[156:159], v[164:167], v[26:29]
	v_mfma_f32_16x16x32_bf16 v[22:25], v[148:151], v[182:185], v[22:25]
	v_mfma_f32_16x16x32_bf16 v[18:21], v[156:159], v[182:185], v[18:21]
	v_mfma_f32_16x16x32_bf16 v[14:17], v[148:151], v[192:195], v[14:17]
	v_mfma_f32_16x16x32_bf16 v[10:13], v[156:159], v[192:195], v[10:13]
	v_mfma_f32_16x16x32_bf16 v[6:9], v[148:151], v[204:207], v[6:9]
	v_mfma_f32_16x16x32_bf16 v[2:5], v[156:159], v[204:207], v[2:5]
	v_mfma_f32_16x16x32_bf16 v[30:33], v[152:155], v[178:181], v[30:33]
	v_mfma_f32_16x16x32_bf16 v[26:29], v[160:163], v[178:181], v[26:29]
	v_mfma_f32_16x16x32_bf16 v[22:25], v[152:155], v[188:191], v[22:25]
	v_mfma_f32_16x16x32_bf16 v[18:21], v[160:163], v[188:191], v[18:21]
	v_mfma_f32_16x16x32_bf16 v[14:17], v[152:155], v[196:199], v[14:17]
	v_mfma_f32_16x16x32_bf16 v[10:13], v[160:163], v[196:199], v[10:13]
	v_mfma_f32_16x16x32_bf16 v[6:9], v[152:155], v[208:211], v[6:9]
	v_mfma_f32_16x16x32_bf16 v[2:5], v[160:163], v[208:211], v[2:5]
	s_setprio 0
	s_barrier
	s_add_i32 s58, 0, 0x18000
	s_add_i32 s59, 0, 0x1c000
	v_add_u32_e32 v144, s58, v186
	v_add_u32_e32 v160, s59, v186
	ds_read_b128 v[132:135], v144
	ds_read_b128 v[136:139], v144 offset:1024
	ds_read_b128 v[140:143], v144 offset:2048
	ds_read_b128 v[144:147], v144 offset:3072
	ds_read_b128 v[148:151], v160
	ds_read_b128 v[152:155], v160 offset:1024
	ds_read_b128 v[156:159], v160 offset:2048
	ds_read_b128 v[160:163], v160 offset:3072
	s_add_u32 s48, s54, 0xb0000
	s_addc_u32 s49, s55, 0
	s_mov_b32 m0, s8
	v_lshl_add_u64 v[222:223], s[48:49], 0, v[172:173]
	ds_read_b128 v[164:167], v187 offset:32768
	ds_read_b128 v[178:181], v187 offset:33792
	ds_read_b128 v[182:185], v187 offset:34816
	ds_read_b128 v[188:191], v187 offset:35840
	ds_read_b128 v[192:195], v187 offset:36864
	ds_read_b128 v[196:199], v187 offset:37888
	ds_read_b128 v[204:207], v187 offset:38912
	ds_read_b128 v[208:211], v187 offset:39936
	s_setprio 1
	global_load_lds_dwordx4 v[222:223], off
	v_lshl_add_u64 v[222:223], s[48:49], 0, v[170:171]
	s_mov_b32 m0, s9
	s_nop 0
	global_load_lds_dwordx4 v[222:223], off
	s_waitcnt vmcnt(8) lgkmcnt(0)
	s_barrier
	v_mfma_f32_16x16x32_bf16 v[128:131], v[132:135], v[164:167], v[128:131]
	v_mfma_f32_16x16x32_bf16 v[124:127], v[140:143], v[164:167], v[124:127]
	v_mfma_f32_16x16x32_bf16 v[120:123], v[132:135], v[182:185], v[120:123]
	v_mfma_f32_16x16x32_bf16 v[116:119], v[140:143], v[182:185], v[116:119]
	v_mfma_f32_16x16x32_bf16 v[112:115], v[132:135], v[192:195], v[112:115]
	v_mfma_f32_16x16x32_bf16 v[108:111], v[140:143], v[192:195], v[108:111]
	v_mfma_f32_16x16x32_bf16 v[104:107], v[132:135], v[204:207], v[104:107]
	v_mfma_f32_16x16x32_bf16 v[100:103], v[140:143], v[204:207], v[100:103]
	v_mfma_f32_16x16x32_bf16 v[128:131], v[136:139], v[178:181], v[128:131]
	v_mfma_f32_16x16x32_bf16 v[124:127], v[144:147], v[178:181], v[124:127]
	v_mfma_f32_16x16x32_bf16 v[120:123], v[136:139], v[188:191], v[120:123]
	v_mfma_f32_16x16x32_bf16 v[116:119], v[144:147], v[188:191], v[116:119]
	v_mfma_f32_16x16x32_bf16 v[112:115], v[136:139], v[196:199], v[112:115]
	v_mfma_f32_16x16x32_bf16 v[108:111], v[144:147], v[196:199], v[108:111]
	v_mfma_f32_16x16x32_bf16 v[104:107], v[136:139], v[208:211], v[104:107]
	v_mfma_f32_16x16x32_bf16 v[100:103], v[144:147], v[208:211], v[100:103]
	s_setprio 0
	s_setprio 1
	v_mfma_f32_16x16x32_bf16 v[62:65], v[148:151], v[164:167], v[62:65]
	v_mfma_f32_16x16x32_bf16 v[58:61], v[156:159], v[164:167], v[58:61]
	v_mfma_f32_16x16x32_bf16 v[54:57], v[148:151], v[182:185], v[54:57]
	v_mfma_f32_16x16x32_bf16 v[50:53], v[156:159], v[182:185], v[50:53]
	v_mfma_f32_16x16x32_bf16 v[46:49], v[148:151], v[192:195], v[46:49]
	v_mfma_f32_16x16x32_bf16 v[42:45], v[156:159], v[192:195], v[42:45]
	v_mfma_f32_16x16x32_bf16 v[38:41], v[148:151], v[204:207], v[38:41]
	v_mfma_f32_16x16x32_bf16 v[34:37], v[156:159], v[204:207], v[34:37]
	v_mfma_f32_16x16x32_bf16 v[62:65], v[152:155], v[178:181], v[62:65]
	v_mfma_f32_16x16x32_bf16 v[58:61], v[160:163], v[178:181], v[58:61]
	v_mfma_f32_16x16x32_bf16 v[54:57], v[152:155], v[188:191], v[54:57]
	v_mfma_f32_16x16x32_bf16 v[50:53], v[160:163], v[188:191], v[50:53]
	v_mfma_f32_16x16x32_bf16 v[46:49], v[152:155], v[196:199], v[46:49]
	v_mfma_f32_16x16x32_bf16 v[42:45], v[160:163], v[196:199], v[42:45]
	v_mfma_f32_16x16x32_bf16 v[38:41], v[152:155], v[208:211], v[38:41]
	v_mfma_f32_16x16x32_bf16 v[34:37], v[160:163], v[208:211], v[34:37]
	s_barrier
	s_add_i32 s48, s58, s2
	v_lshl_add_u64 v[214:215], v[214:215], 0, s[28:29]
	s_mov_b32 m0, s48
	ds_read_b128 v[164:167], v187 offset:49152
	ds_read_b128 v[178:181], v187 offset:50176
	ds_read_b128 v[182:185], v187 offset:51200
	ds_read_b128 v[188:191], v187 offset:52224
	ds_read_b128 v[192:195], v187 offset:53248
	ds_read_b128 v[196:199], v187 offset:54272
	ds_read_b128 v[204:207], v187 offset:55296
	ds_read_b128 v[208:211], v187 offset:56320
	global_load_lds_dwordx4 v[214:215], off
	s_add_i32 m0, s48, 0x2000
	s_add_u32 s48, s52, 0xb0080
	v_lshl_add_u64 v[214:215], v[216:217], 0, s[28:29]
	s_addc_u32 s49, s53, 0
	s_add_i32 s52, s59, s2
	global_load_lds_dwordx4 v[214:215], off
	v_lshl_add_u64 v[214:215], s[48:49], 0, v[98:99]
	s_mov_b32 m0, s52
	s_nop 0
	global_load_lds_dwordx4 v[214:215], off
	v_lshl_add_u64 v[214:215], s[48:49], 0, v[168:169]
	s_add_i32 m0, s52, 0x2000
	s_nop 0
	global_load_lds_dwordx4 v[214:215], off
	v_lshl_add_u64 v[214:215], v[218:219], 0, s[28:29]
	s_mov_b32 m0, s12
	s_nop 0
	global_load_lds_dwordx4 v[214:215], off
	v_lshl_add_u64 v[214:215], v[220:221], 0, s[28:29]
	s_mov_b32 m0, s13
	s_nop 0
	global_load_lds_dwordx4 v[214:215], off
	s_waitcnt vmcnt(8) lgkmcnt(0)
	s_barrier
	v_mfma_f32_16x16x32_bf16 v[94:97], v[132:135], v[164:167], v[94:97]
	v_mfma_f32_16x16x32_bf16 v[90:93], v[140:143], v[164:167], v[90:93]
	v_mfma_f32_16x16x32_bf16 v[86:89], v[132:135], v[182:185], v[86:89]
	v_mfma_f32_16x16x32_bf16 v[82:85], v[140:143], v[182:185], v[82:85]
	v_mfma_f32_16x16x32_bf16 v[78:81], v[132:135], v[192:195], v[78:81]
	v_mfma_f32_16x16x32_bf16 v[74:77], v[140:143], v[192:195], v[74:77]
	v_mfma_f32_16x16x32_bf16 v[70:73], v[132:135], v[204:207], v[70:73]
	v_mfma_f32_16x16x32_bf16 v[66:69], v[140:143], v[204:207], v[66:69]
	v_mfma_f32_16x16x32_bf16 v[94:97], v[136:139], v[178:181], v[94:97]
	v_mfma_f32_16x16x32_bf16 v[90:93], v[144:147], v[178:181], v[90:93]
	v_mfma_f32_16x16x32_bf16 v[86:89], v[136:139], v[188:191], v[86:89]
	v_mfma_f32_16x16x32_bf16 v[82:85], v[144:147], v[188:191], v[82:85]
	v_mfma_f32_16x16x32_bf16 v[78:81], v[136:139], v[196:199], v[78:81]
	v_mfma_f32_16x16x32_bf16 v[74:77], v[144:147], v[196:199], v[74:77]
	v_mfma_f32_16x16x32_bf16 v[70:73], v[136:139], v[208:211], v[70:73]
	v_mfma_f32_16x16x32_bf16 v[66:69], v[144:147], v[208:211], v[66:69]
	s_setprio 0
	s_setprio 1
	v_mfma_f32_16x16x32_bf16 v[30:33], v[148:151], v[164:167], v[30:33]
	v_mfma_f32_16x16x32_bf16 v[26:29], v[156:159], v[164:167], v[26:29]
	v_mfma_f32_16x16x32_bf16 v[22:25], v[148:151], v[182:185], v[22:25]
	v_mfma_f32_16x16x32_bf16 v[18:21], v[156:159], v[182:185], v[18:21]
	v_mfma_f32_16x16x32_bf16 v[14:17], v[148:151], v[192:195], v[14:17]
	v_mfma_f32_16x16x32_bf16 v[10:13], v[156:159], v[192:195], v[10:13]
	v_mfma_f32_16x16x32_bf16 v[6:9], v[148:151], v[204:207], v[6:9]
	v_mfma_f32_16x16x32_bf16 v[2:5], v[156:159], v[204:207], v[2:5]
	v_mfma_f32_16x16x32_bf16 v[30:33], v[152:155], v[178:181], v[30:33]
	v_mfma_f32_16x16x32_bf16 v[26:29], v[160:163], v[178:181], v[26:29]
	v_mfma_f32_16x16x32_bf16 v[22:25], v[152:155], v[188:191], v[22:25]
	v_mfma_f32_16x16x32_bf16 v[18:21], v[160:163], v[188:191], v[18:21]
	v_mfma_f32_16x16x32_bf16 v[14:17], v[152:155], v[196:199], v[14:17]
	v_mfma_f32_16x16x32_bf16 v[10:13], v[160:163], v[196:199], v[10:13]
	v_mfma_f32_16x16x32_bf16 v[6:9], v[152:155], v[208:211], v[6:9]
	v_mfma_f32_16x16x32_bf16 v[2:5], v[160:163], v[208:211], v[2:5]
	s_setprio 0
	s_barrier
	s_add_i32 s57, s57, 2
	s_add_u32 s33, s33, 0x100
	s_addc_u32 s56, s56, 0
	s_cmp_gt_u32 s57, 41
	s_mov_b64 s[48:49], s[50:51]
	s_cbranch_scc0 .LBB0_1529
	s_and_b64 vcc, exec, s[44:45]
	s_cbranch_vccz .LBB0_1532
	s_barrier

.LBB0_1553:
	s_add_i32 s63, s54, 2
	s_add_u32 s52, s50, 0x100
	s_addc_u32 s53, s51, 0
	s_add_i32 s64, 0, 0x10000
	s_cmp_eq_u32 s60, s54
	s_cselect_b32 s57, s45, s53
	s_cselect_b32 s56, s44, s52
	s_cselect_b32 s55, s47, s62
	s_cselect_b32 s54, s46, s61
	s_add_i32 s65, 0, 0x14000
	v_add_u32_e32 v144, s64, v198
	v_add_u32_e32 v160, s65, v198
	s_waitcnt lgkmcnt(0)
	ds_read_b128 v[132:135], v144
	ds_read_b128 v[136:139], v144 offset:1024
	ds_read_b128 v[140:143], v144 offset:2048
	ds_read_b128 v[144:147], v144 offset:3072
	ds_read_b128 v[148:151], v160
	ds_read_b128 v[152:155], v160 offset:1024
	ds_read_b128 v[156:159], v160 offset:2048
	ds_read_b128 v[160:163], v160 offset:3072
	v_lshl_add_u64 v[214:215], s[50:51], 0, v[178:179]
	s_add_i32 m0, s4, 0xc000
	ds_read_b128 v[164:167], v199
	ds_read_b128 v[168:171], v199 offset:1024
	ds_read_b128 v[182:185], v199 offset:2048
	ds_read_b128 v[186:189], v199 offset:3072
	ds_read_b128 v[190:193], v199 offset:4096
	ds_read_b128 v[194:197], v199 offset:5120
	ds_read_b128 v[204:207], v199 offset:6144
	ds_read_b128 v[208:211], v199 offset:7168
	s_setprio 1
	global_load_lds_dwordx4 v[214:215], off
	v_lshl_add_u64 v[214:215], s[50:51], 0, v[180:181]
	s_add_i32 m0, s4, 0xe000
	s_nop 0
	global_load_lds_dwordx4 v[214:215], off
	s_waitcnt vmcnt(8) lgkmcnt(0)
	s_barrier
	v_mfma_f32_16x16x32_bf16 v[128:131], v[132:135], v[164:167], v[128:131]
	v_mfma_f32_16x16x32_bf16 v[124:127], v[140:143], v[164:167], v[124:127]
	v_mfma_f32_16x16x32_bf16 v[120:123], v[132:135], v[182:185], v[120:123]
	v_mfma_f32_16x16x32_bf16 v[116:119], v[140:143], v[182:185], v[116:119]
	v_mfma_f32_16x16x32_bf16 v[104:107], v[132:135], v[190:193], v[104:107]
	v_mfma_f32_16x16x32_bf16 v[100:103], v[140:143], v[190:193], v[100:103]
	v_mfma_f32_16x16x32_bf16 v[86:89], v[132:135], v[204:207], v[86:89]
	v_mfma_f32_16x16x32_bf16 v[82:85], v[140:143], v[204:207], v[82:85]
	v_mfma_f32_16x16x32_bf16 v[128:131], v[136:139], v[168:171], v[128:131]
	v_mfma_f32_16x16x32_bf16 v[124:127], v[144:147], v[168:171], v[124:127]
	v_mfma_f32_16x16x32_bf16 v[120:123], v[136:139], v[186:189], v[120:123]
	v_mfma_f32_16x16x32_bf16 v[116:119], v[144:147], v[186:189], v[116:119]
	v_mfma_f32_16x16x32_bf16 v[104:107], v[136:139], v[194:197], v[104:107]
	v_mfma_f32_16x16x32_bf16 v[100:103], v[144:147], v[194:197], v[100:103]
	v_mfma_f32_16x16x32_bf16 v[86:89], v[136:139], v[208:211], v[86:89]
	v_mfma_f32_16x16x32_bf16 v[82:85], v[144:147], v[208:211], v[82:85]
	s_setprio 0
	s_setprio 1
	v_mfma_f32_16x16x32_bf16 v[112:115], v[148:151], v[164:167], v[112:115]
	v_mfma_f32_16x16x32_bf16 v[108:111], v[156:159], v[164:167], v[108:111]
	v_mfma_f32_16x16x32_bf16 v[94:97], v[148:151], v[182:185], v[94:97]
	v_mfma_f32_16x16x32_bf16 v[90:93], v[156:159], v[182:185], v[90:93]
	v_mfma_f32_16x16x32_bf16 v[78:81], v[148:151], v[190:193], v[78:81]
	v_mfma_f32_16x16x32_bf16 v[74:77], v[156:159], v[190:193], v[74:77]
	v_mfma_f32_16x16x32_bf16 v[70:73], v[148:151], v[204:207], v[70:73]
	v_mfma_f32_16x16x32_bf16 v[66:69], v[156:159], v[204:207], v[66:69]
	v_mfma_f32_16x16x32_bf16 v[112:115], v[152:155], v[168:171], v[112:115]
	v_mfma_f32_16x16x32_bf16 v[108:111], v[160:163], v[168:171], v[108:111]
	v_mfma_f32_16x16x32_bf16 v[94:97], v[152:155], v[186:189], v[94:97]
	v_mfma_f32_16x16x32_bf16 v[90:93], v[160:163], v[186:189], v[90:93]
	v_mfma_f32_16x16x32_bf16 v[78:81], v[152:155], v[194:197], v[78:81]
	v_mfma_f32_16x16x32_bf16 v[74:77], v[160:163], v[194:197], v[74:77]
	v_mfma_f32_16x16x32_bf16 v[70:73], v[152:155], v[208:211], v[70:73]
	v_mfma_f32_16x16x32_bf16 v[66:69], v[160:163], v[208:211], v[66:69]
	s_barrier
	s_add_i32 s50, s64, s2
	v_lshl_add_u64 v[214:215], s[54:55], 0, v[98:99]
	s_mov_b32 m0, s50
	ds_read_b128 v[164:167], v199 offset:16384
	ds_read_b128 v[168:171], v199 offset:17408
	ds_read_b128 v[182:185], v199 offset:18432
	ds_read_b128 v[186:189], v199 offset:19456
	ds_read_b128 v[190:193], v199 offset:20480
	ds_read_b128 v[194:197], v199 offset:21504
	ds_read_b128 v[204:207], v199 offset:22528
	ds_read_b128 v[208:211], v199 offset:23552
	global_load_lds_dwordx4 v[214:215], off
	s_add_i32 m0, s50, 0x2000
	s_add_u32 s50, s54, 0xb0000
	v_lshl_add_u64 v[216:217], s[54:55], 0, v[172:173]
	s_addc_u32 s51, s55, 0
	s_add_i32 s64, s65, s2
	global_load_lds_dwordx4 v[216:217], off
	v_lshl_add_u64 v[218:219], s[50:51], 0, v[98:99]
	s_mov_b32 m0, s64
	v_lshl_add_u64 v[220:221], s[56:57], 0, v[174:175]
	global_load_lds_dwordx4 v[218:219], off
	v_lshl_add_u64 v[218:219], s[50:51], 0, v[172:173]
	s_add_i32 m0, s64, 0x2000
	s_nop 0
	global_load_lds_dwordx4 v[218:219], off
	v_lshl_add_u64 v[218:219], s[56:57], 0, v[176:177]
	s_mov_b32 m0, s4
	s_nop 0
	global_load_lds_dwordx4 v[218:219], off
	s_mov_b32 m0, s7
	s_nop 0
	global_load_lds_dwordx4 v[220:221], off
	s_waitcnt vmcnt(8) lgkmcnt(0)
	s_barrier
	v_mfma_f32_16x16x32_bf16 v[62:65], v[132:135], v[164:167], v[62:65]
	v_mfma_f32_16x16x32_bf16 v[58:61], v[140:143], v[164:167], v[58:61]
	v_mfma_f32_16x16x32_bf16 v[54:57], v[132:135], v[182:185], v[54:57]
	v_mfma_f32_16x16x32_bf16 v[50:53], v[140:143], v[182:185], v[50:53]
	v_mfma_f32_16x16x32_bf16 v[38:41], v[132:135], v[190:193], v[38:41]
	v_mfma_f32_16x16x32_bf16 v[34:37], v[140:143], v[190:193], v[34:37]
	v_mfma_f32_16x16x32_bf16 v[22:25], v[132:135], v[204:207], v[22:25]
	v_mfma_f32_16x16x32_bf16 v[18:21], v[140:143], v[204:207], v[18:21]
	v_mfma_f32_16x16x32_bf16 v[62:65], v[136:139], v[168:171], v[62:65]
	v_mfma_f32_16x16x32_bf16 v[58:61], v[144:147], v[168:171], v[58:61]
	v_mfma_f32_16x16x32_bf16 v[54:57], v[136:139], v[186:189], v[54:57]
	v_mfma_f32_16x16x32_bf16 v[50:53], v[144:147], v[186:189], v[50:53]
	v_mfma_f32_16x16x32_bf16 v[38:41], v[136:139], v[194:197], v[38:41]
	v_mfma_f32_16x16x32_bf16 v[34:37], v[144:147], v[194:197], v[34:37]
	v_mfma_f32_16x16x32_bf16 v[22:25], v[136:139], v[208:211], v[22:25]
	v_mfma_f32_16x16x32_bf16 v[18:21], v[144:147], v[208:211], v[18:21]
	s_setprio 0
	s_setprio 1
	v_mfma_f32_16x16x32_bf16 v[46:49], v[148:151], v[164:167], v[46:49]
	v_mfma_f32_16x16x32_bf16 v[42:45], v[156:159], v[164:167], v[42:45]
	v_mfma_f32_16x16x32_bf16 v[30:33], v[148:151], v[182:185], v[30:33]
	v_mfma_f32_16x16x32_bf16 v[26:29], v[156:159], v[182:185], v[26:29]
	v_mfma_f32_16x16x32_bf16 v[14:17], v[148:151], v[190:193], v[14:17]
	v_mfma_f32_16x16x32_bf16 v[10:13], v[156:159], v[190:193], v[10:13]
	v_mfma_f32_16x16x32_bf16 v[6:9], v[148:151], v[204:207], v[6:9]
	v_mfma_f32_16x16x32_bf16 v[2:5], v[156:159], v[204:207], v[2:5]
	v_mfma_f32_16x16x32_bf16 v[46:49], v[152:155], v[168:171], v[46:49]
	v_mfma_f32_16x16x32_bf16 v[42:45], v[160:163], v[168:171], v[42:45]
	v_mfma_f32_16x16x32_bf16 v[30:33], v[152:155], v[186:189], v[30:33]
	v_mfma_f32_16x16x32_bf16 v[26:29], v[160:163], v[186:189], v[26:29]
	v_mfma_f32_16x16x32_bf16 v[14:17], v[152:155], v[194:197], v[14:17]
	v_mfma_f32_16x16x32_bf16 v[10:13], v[160:163], v[194:197], v[10:13]
	v_mfma_f32_16x16x32_bf16 v[6:9], v[152:155], v[208:211], v[6:9]
	v_mfma_f32_16x16x32_bf16 v[2:5], v[160:163], v[208:211], v[2:5]
	s_setprio 0
	s_barrier
	s_add_i32 s64, 0, 0x18000
	s_add_i32 s65, 0, 0x1c000
	v_add_u32_e32 v144, s64, v198
	v_add_u32_e32 v160, s65, v198
	ds_read_b128 v[132:135], v144
	ds_read_b128 v[136:139], v144 offset:1024
	ds_read_b128 v[140:143], v144 offset:2048
	ds_read_b128 v[144:147], v144 offset:3072
	ds_read_b128 v[148:151], v160
	ds_read_b128 v[152:155], v160 offset:1024
	ds_read_b128 v[156:159], v160 offset:2048
	ds_read_b128 v[160:163], v160 offset:3072
	s_add_u32 s50, s56, 0xb0000
	s_addc_u32 s51, s57, 0
	s_mov_b32 m0, s8
	v_lshl_add_u64 v[222:223], s[50:51], 0, v[176:177]
	ds_read_b128 v[164:167], v199 offset:32768
	ds_read_b128 v[168:171], v199 offset:33792
	ds_read_b128 v[182:185], v199 offset:34816
	ds_read_b128 v[186:189], v199 offset:35840
	ds_read_b128 v[190:193], v199 offset:36864
	ds_read_b128 v[194:197], v199 offset:37888
	ds_read_b128 v[204:207], v199 offset:38912
	ds_read_b128 v[208:211], v199 offset:39936
	s_setprio 1
	global_load_lds_dwordx4 v[222:223], off
	v_lshl_add_u64 v[222:223], s[50:51], 0, v[174:175]
	s_mov_b32 m0, s9
	s_nop 0
	global_load_lds_dwordx4 v[222:223], off
	s_waitcnt vmcnt(8) lgkmcnt(0)
	s_barrier
	v_mfma_f32_16x16x32_bf16 v[128:131], v[132:135], v[164:167], v[128:131]
	v_mfma_f32_16x16x32_bf16 v[124:127], v[140:143], v[164:167], v[124:127]
	v_mfma_f32_16x16x32_bf16 v[120:123], v[132:135], v[182:185], v[120:123]
	v_mfma_f32_16x16x32_bf16 v[116:119], v[140:143], v[182:185], v[116:119]
	v_mfma_f32_16x16x32_bf16 v[104:107], v[132:135], v[190:193], v[104:107]
	v_mfma_f32_16x16x32_bf16 v[100:103], v[140:143], v[190:193], v[100:103]
	v_mfma_f32_16x16x32_bf16 v[86:89], v[132:135], v[204:207], v[86:89]
	v_mfma_f32_16x16x32_bf16 v[82:85], v[140:143], v[204:207], v[82:85]
	v_mfma_f32_16x16x32_bf16 v[128:131], v[136:139], v[168:171], v[128:131]
	v_mfma_f32_16x16x32_bf16 v[124:127], v[144:147], v[168:171], v[124:127]
	v_mfma_f32_16x16x32_bf16 v[120:123], v[136:139], v[186:189], v[120:123]
	v_mfma_f32_16x16x32_bf16 v[116:119], v[144:147], v[186:189], v[116:119]
	v_mfma_f32_16x16x32_bf16 v[104:107], v[136:139], v[194:197], v[104:107]
	v_mfma_f32_16x16x32_bf16 v[100:103], v[144:147], v[194:197], v[100:103]
	v_mfma_f32_16x16x32_bf16 v[86:89], v[136:139], v[208:211], v[86:89]
	v_mfma_f32_16x16x32_bf16 v[82:85], v[144:147], v[208:211], v[82:85]
	s_setprio 0
	s_setprio 1
	v_mfma_f32_16x16x32_bf16 v[112:115], v[148:151], v[164:167], v[112:115]
	v_mfma_f32_16x16x32_bf16 v[108:111], v[156:159], v[164:167], v[108:111]
	v_mfma_f32_16x16x32_bf16 v[94:97], v[148:151], v[182:185], v[94:97]
	v_mfma_f32_16x16x32_bf16 v[90:93], v[156:159], v[182:185], v[90:93]
	v_mfma_f32_16x16x32_bf16 v[78:81], v[148:151], v[190:193], v[78:81]
	v_mfma_f32_16x16x32_bf16 v[74:77], v[156:159], v[190:193], v[74:77]
	v_mfma_f32_16x16x32_bf16 v[70:73], v[148:151], v[204:207], v[70:73]
	v_mfma_f32_16x16x32_bf16 v[66:69], v[156:159], v[204:207], v[66:69]
	v_mfma_f32_16x16x32_bf16 v[112:115], v[152:155], v[168:171], v[112:115]
	v_mfma_f32_16x16x32_bf16 v[108:111], v[160:163], v[168:171], v[108:111]
	v_mfma_f32_16x16x32_bf16 v[94:97], v[152:155], v[186:189], v[94:97]
	v_mfma_f32_16x16x32_bf16 v[90:93], v[160:163], v[186:189], v[90:93]
	v_mfma_f32_16x16x32_bf16 v[78:81], v[152:155], v[194:197], v[78:81]
	v_mfma_f32_16x16x32_bf16 v[74:77], v[160:163], v[194:197], v[74:77]
	v_mfma_f32_16x16x32_bf16 v[70:73], v[152:155], v[208:211], v[70:73]
	v_mfma_f32_16x16x32_bf16 v[66:69], v[160:163], v[208:211], v[66:69]
	s_barrier
	s_add_i32 s50, s64, s2
	v_lshl_add_u64 v[214:215], v[214:215], 0, s[28:29]
	s_mov_b32 m0, s50
	ds_read_b128 v[164:167], v199 offset:49152
	ds_read_b128 v[168:171], v199 offset:50176
	ds_read_b128 v[182:185], v199 offset:51200
	ds_read_b128 v[186:189], v199 offset:52224
	ds_read_b128 v[190:193], v199 offset:53248
	ds_read_b128 v[194:197], v199 offset:54272
	ds_read_b128 v[204:207], v199 offset:55296
	ds_read_b128 v[208:211], v199 offset:56320
	global_load_lds_dwordx4 v[214:215], off
	s_add_i32 m0, s50, 0x2000
	s_add_u32 s50, s54, 0xb0080
	v_lshl_add_u64 v[214:215], v[216:217], 0, s[28:29]
	s_addc_u32 s51, s55, 0
	s_add_i32 s54, s65, s2
	global_load_lds_dwordx4 v[214:215], off
	v_lshl_add_u64 v[214:215], s[50:51], 0, v[98:99]
	s_mov_b32 m0, s54
	s_nop 0
	global_load_lds_dwordx4 v[214:215], off
	v_lshl_add_u64 v[214:215], s[50:51], 0, v[172:173]
	s_add_i32 m0, s54, 0x2000
	s_nop 0
	global_load_lds_dwordx4 v[214:215], off
	v_lshl_add_u64 v[214:215], v[218:219], 0, s[28:29]
	s_mov_b32 m0, s12
	s_nop 0
	global_load_lds_dwordx4 v[214:215], off
	v_lshl_add_u64 v[214:215], v[220:221], 0, s[28:29]
	s_mov_b32 m0, s13
	s_nop 0
	global_load_lds_dwordx4 v[214:215], off
	s_waitcnt vmcnt(8) lgkmcnt(0)
	s_barrier
	v_mfma_f32_16x16x32_bf16 v[62:65], v[132:135], v[164:167], v[62:65]
	v_mfma_f32_16x16x32_bf16 v[58:61], v[140:143], v[164:167], v[58:61]
	v_mfma_f32_16x16x32_bf16 v[54:57], v[132:135], v[182:185], v[54:57]
	v_mfma_f32_16x16x32_bf16 v[50:53], v[140:143], v[182:185], v[50:53]
	v_mfma_f32_16x16x32_bf16 v[38:41], v[132:135], v[190:193], v[38:41]
	v_mfma_f32_16x16x32_bf16 v[34:37], v[140:143], v[190:193], v[34:37]
	v_mfma_f32_16x16x32_bf16 v[22:25], v[132:135], v[204:207], v[22:25]
	v_mfma_f32_16x16x32_bf16 v[18:21], v[140:143], v[204:207], v[18:21]
	v_mfma_f32_16x16x32_bf16 v[62:65], v[136:139], v[168:171], v[62:65]
	v_mfma_f32_16x16x32_bf16 v[58:61], v[144:147], v[168:171], v[58:61]
	v_mfma_f32_16x16x32_bf16 v[54:57], v[136:139], v[186:189], v[54:57]
	v_mfma_f32_16x16x32_bf16 v[50:53], v[144:147], v[186:189], v[50:53]
	v_mfma_f32_16x16x32_bf16 v[38:41], v[136:139], v[194:197], v[38:41]
	v_mfma_f32_16x16x32_bf16 v[34:37], v[144:147], v[194:197], v[34:37]
	v_mfma_f32_16x16x32_bf16 v[22:25], v[136:139], v[208:211], v[22:25]
	v_mfma_f32_16x16x32_bf16 v[18:21], v[144:147], v[208:211], v[18:21]
	s_setprio 0
	s_setprio 1
	v_mfma_f32_16x16x32_bf16 v[46:49], v[148:151], v[164:167], v[46:49]
	v_mfma_f32_16x16x32_bf16 v[42:45], v[156:159], v[164:167], v[42:45]
	v_mfma_f32_16x16x32_bf16 v[30:33], v[148:151], v[182:185], v[30:33]
	v_mfma_f32_16x16x32_bf16 v[26:29], v[156:159], v[182:185], v[26:29]
	v_mfma_f32_16x16x32_bf16 v[14:17], v[148:151], v[190:193], v[14:17]
	v_mfma_f32_16x16x32_bf16 v[10:13], v[156:159], v[190:193], v[10:13]
	v_mfma_f32_16x16x32_bf16 v[6:9], v[148:151], v[204:207], v[6:9]
	v_mfma_f32_16x16x32_bf16 v[2:5], v[156:159], v[204:207], v[2:5]
	v_mfma_f32_16x16x32_bf16 v[46:49], v[152:155], v[168:171], v[46:49]
	v_mfma_f32_16x16x32_bf16 v[42:45], v[160:163], v[168:171], v[42:45]
	v_mfma_f32_16x16x32_bf16 v[30:33], v[152:155], v[186:189], v[30:33]
	v_mfma_f32_16x16x32_bf16 v[26:29], v[160:163], v[186:189], v[26:29]
	v_mfma_f32_16x16x32_bf16 v[14:17], v[152:155], v[194:197], v[14:17]
	v_mfma_f32_16x16x32_bf16 v[10:13], v[160:163], v[194:197], v[10:13]
	v_mfma_f32_16x16x32_bf16 v[6:9], v[152:155], v[208:211], v[6:9]
	v_mfma_f32_16x16x32_bf16 v[2:5], v[160:163], v[208:211], v[2:5]
	s_setprio 0
	s_barrier
	s_add_u32 s61, s61, 0x100
	s_addc_u32 s62, s62, 0
	s_cmp_ge_i32 s63, s59
	s_mov_b64 s[50:51], s[52:53]
	s_mov_b32 s54, s63
	s_cbranch_scc0 .LBB0_1553
	s_and_b64 vcc, exec, s[42:43]
	s_cbranch_vccz .LBB0_1556
	s_barrier
